# conv fill batching plus GEMM loop-edge rotation (4 loops) plus all per-block s_setprio flips removed
# speedup vs baseline: 1.0081x; 1.0081x over previous
; #define PG8_STAGE(bufoff, gbase, voff) do { _Pragma("unroll") for (int _i = 0; _i < 2; ++_i) \
;         __builtin_amdgcn_global_load_lds((const unsigned*)((const char*)(gbase) + (voff)[_i]), (PG8_LAS unsigned*)(lds + (bufoff) + ldsw + _i * 8192), 16, 0, 0); } while (0)
; #define PG8_LDA(dst, b, h) do { _Pragma("unroll") for (int m = 0; m < 4; ++m) _Pragma("unroll") for (int k = 0; k < 2; ++k) dst[m][k] = *(const PG8_LAS bf16x8*)(lds + PG8_SA(b, h) + aoff + m * 2048 + k * 1024); } while (0)
; #define PG8_LDB(dst, b, h) do { _Pragma("unroll") for (int n = 0; n < 2; ++n) _Pragma("unroll") for (int k = 0; k < 2; ++k) dst[n][k] = *(const PG8_LAS bf16x8*)(lds + PG8_SB(b, h) + boff + n * 2048 + k * 1024); } while (0)
; #define PG8_MMA(ai, bj, At, Bt) do { __builtin_amdgcn_s_setprio(1); _Pragma("unroll") for (int m = 0; m < 4; ++m) _Pragma("unroll") for (int n = 0; n < 2; ++n) _Pragma("unroll") for (int k = 0; k < 2; ++k) \
;         acc[ai][bj][m][n] = __builtin_amdgcn_mfma_f32_16x16x32_bf16(Bt[n][k], At[m][k], acc[ai][bj][m][n], 0, 0, 0); __builtin_amdgcn_s_setprio(0); } while (0)
; #define PG8_WAIT_V(n) asm volatile("s_waitcnt vmcnt(" #n ")" ::: "memory")
; #define PG8_WAIT_L(n) asm volatile("s_waitcnt lgkmcnt(" #n ")" ::: "memory")
; #define PG8_BAR __builtin_amdgcn_s_barrier()
; #define PG8_SCHED __builtin_amdgcn_sched_barrier(0)
; template <class Epi, class Sched, bool ALIGN_EPI = false, bool SP2 = false>
; __device__ __forceinline__ void gemm_phase(PG8_LAS unsigned char* lds, const Gemm g, const Sched& S, const Epi& E) {
;     ...
;             PG8_LDB(B0, 0, 0); PG8_LDB(B1, 0, 1); PG8_SCHED; PG8_LDA(At, 0, 0); PG8_STAGE(PG8_SA(1, 1), a1 + hstepA, voffA);
;             PG8_WAIT_V(8); PG8_WAIT_L(0); PG8_BAR; PG8_MMA(0, 0, At, B0); PG8_MMA(0, 1, At, B1); PG8_BAR; PG8_SCHED;
;             PG8_LDA(At, 0, 1); PG8_STAGE(PG8_SB(0, 0), b2, voffB); PG8_STAGE(PG8_SB(0, 1), b2 + hstepB, voffB); PG8_STAGE(PG8_SA(0, 0), a2, voffA);
;             PG8_WAIT_V(8); PG8_WAIT_L(0); PG8_BAR; PG8_MMA(1, 0, At, B0); PG8_MMA(1, 1, At, B1); PG8_BAR; PG8_SCHED;
.Lgk_146:
	ds_read_b128 v[164:167], v130
	ds_read_b128 v[168:171], v130 offset:1024
	ds_read_b128 v[186:189], v130 offset:2048
	ds_read_b128 v[190:193], v130 offset:3072
	v_add_u32_e32 v130, s81, v161
	ds_read_b128 v[198:201], v130
	ds_read_b128 v[202:205], v130 offset:1024
	ds_read_b128 v[206:209], v130 offset:2048
	ds_read_b128 v[210:213], v130 offset:3072
	v_lshl_add_u64 v[172:173], s[46:47], 0, v[156:157]
	s_add_i32 m0, s9, 0xc000
	ds_read_b128 v[214:217], v163
	ds_read_b128 v[218:221], v163 offset:1024
	ds_read_b128 v[222:225], v163 offset:2048
	ds_read_b128 v[226:229], v163 offset:3072
	ds_read_b128 v[230:233], v163 offset:4096
	ds_read_b128 v[234:237], v163 offset:5120
	ds_read_b128 v[238:241], v163 offset:6144
	ds_read_b128 v[242:245], v163 offset:7168
	global_load_lds_dwordx4 v[172:173], off
	v_lshl_add_u64 v[172:173], s[46:47], 0, v[158:159]
	s_add_i32 m0, s9, 0xe000
	s_nop 0
	global_load_lds_dwordx4 v[172:173], off
	s_waitcnt vmcnt(8)
	s_waitcnt lgkmcnt(0)
	s_barrier
	s_waitcnt lgkmcnt(0)
	v_mfma_f32_16x16x32_bf16 v[126:129], v[164:167], v[214:217], v[126:129]
	v_mfma_f32_16x16x32_bf16 v[122:125], v[186:189], v[214:217], v[122:125]
	v_mfma_f32_16x16x32_bf16 v[118:121], v[164:167], v[222:225], v[118:121]
	v_mfma_f32_16x16x32_bf16 v[114:117], v[186:189], v[222:225], v[114:117]
	v_mfma_f32_16x16x32_bf16 v[102:105], v[164:167], v[230:233], v[102:105]
	v_mfma_f32_16x16x32_bf16 v[98:101], v[186:189], v[230:233], v[98:101]
	v_mfma_f32_16x16x32_bf16 v[86:89], v[164:167], v[238:241], v[86:89]
	v_mfma_f32_16x16x32_bf16 v[82:85], v[186:189], v[238:241], v[82:85]
	v_mfma_f32_16x16x32_bf16 v[126:129], v[168:171], v[218:221], v[126:129]
	v_mfma_f32_16x16x32_bf16 v[122:125], v[190:193], v[218:221], v[122:125]
	v_mfma_f32_16x16x32_bf16 v[118:121], v[168:171], v[226:229], v[118:121]
	v_mfma_f32_16x16x32_bf16 v[114:117], v[190:193], v[226:229], v[114:117]
	v_mfma_f32_16x16x32_bf16 v[102:105], v[168:171], v[234:237], v[102:105]
	v_mfma_f32_16x16x32_bf16 v[98:101], v[190:193], v[234:237], v[98:101]
	v_mfma_f32_16x16x32_bf16 v[86:89], v[168:171], v[242:245], v[86:89]
	v_mfma_f32_16x16x32_bf16 v[82:85], v[190:193], v[242:245], v[82:85]
	v_mfma_f32_16x16x32_bf16 v[110:113], v[198:201], v[214:217], v[110:113]
	v_mfma_f32_16x16x32_bf16 v[106:109], v[206:209], v[214:217], v[106:109]
	v_mfma_f32_16x16x32_bf16 v[94:97], v[198:201], v[222:225], v[94:97]
	v_mfma_f32_16x16x32_bf16 v[90:93], v[206:209], v[222:225], v[90:93]
	v_mfma_f32_16x16x32_bf16 v[78:81], v[198:201], v[230:233], v[78:81]
	v_mfma_f32_16x16x32_bf16 v[74:77], v[206:209], v[230:233], v[74:77]
	v_mfma_f32_16x16x32_bf16 v[70:73], v[198:201], v[238:241], v[70:73]
	v_mfma_f32_16x16x32_bf16 v[66:69], v[206:209], v[238:241], v[66:69]
	v_mfma_f32_16x16x32_bf16 v[110:113], v[202:205], v[218:221], v[110:113]
	v_mfma_f32_16x16x32_bf16 v[106:109], v[210:213], v[218:221], v[106:109]
	v_mfma_f32_16x16x32_bf16 v[94:97], v[202:205], v[226:229], v[94:97]
	v_mfma_f32_16x16x32_bf16 v[90:93], v[210:213], v[226:229], v[90:93]
	v_mfma_f32_16x16x32_bf16 v[78:81], v[202:205], v[234:237], v[78:81]
	v_mfma_f32_16x16x32_bf16 v[74:77], v[210:213], v[234:237], v[74:77]
	v_mfma_f32_16x16x32_bf16 v[70:73], v[202:205], v[242:245], v[70:73]
	v_mfma_f32_16x16x32_bf16 v[66:69], v[210:213], v[242:245], v[66:69]
	s_barrier
	s_add_i32 s10, s69, s8
	v_lshl_add_u64 v[172:173], s[48:49], 0, v[0:1]
	s_mov_b32 m0, s10
	ds_read_b128 v[214:217], v163 offset:16384
	ds_read_b128 v[218:221], v163 offset:17408
	ds_read_b128 v[222:225], v163 offset:18432
	ds_read_b128 v[226:229], v163 offset:19456
	ds_read_b128 v[230:233], v163 offset:20480
	ds_read_b128 v[234:237], v163 offset:21504
	ds_read_b128 v[238:241], v163 offset:22528
	ds_read_b128 v[242:245], v163 offset:23552
	global_load_lds_dwordx4 v[172:173], off
	s_add_i32 m0, s10, 0x2000
	s_add_u32 s10, s48, 0x40000
	v_lshl_add_u64 v[246:247], s[48:49], 0, v[150:151]
	s_addc_u32 s11, s49, 0
	s_add_i32 s69, s81, s8
	global_load_lds_dwordx4 v[246:247], off
	v_lshl_add_u64 v[248:249], s[10:11], 0, v[0:1]
	s_mov_b32 m0, s69
	v_lshl_add_u64 v[130:131], s[50:51], 0, v[152:153]
	global_load_lds_dwordx4 v[248:249], off
	v_lshl_add_u64 v[248:249], s[10:11], 0, v[150:151]
	s_add_i32 m0, s69, 0x2000
	s_nop 0
	global_load_lds_dwordx4 v[248:249], off
	v_lshl_add_u64 v[248:249], s[50:51], 0, v[154:155]
	s_mov_b32 m0, s9
	s_nop 0
	global_load_lds_dwordx4 v[248:249], off
	s_mov_b32 m0, s30
	s_nop 0
	global_load_lds_dwordx4 v[130:131], off
	s_waitcnt vmcnt(8)
	s_waitcnt lgkmcnt(0)
	s_barrier
	s_waitcnt lgkmcnt(0)
	v_mfma_f32_16x16x32_bf16 v[62:65], v[164:167], v[214:217], v[62:65]
	v_mfma_f32_16x16x32_bf16 v[58:61], v[186:189], v[214:217], v[58:61]
	v_mfma_f32_16x16x32_bf16 v[54:57], v[164:167], v[222:225], v[54:57]
	v_mfma_f32_16x16x32_bf16 v[50:53], v[186:189], v[222:225], v[50:53]
	v_mfma_f32_16x16x32_bf16 v[38:41], v[164:167], v[230:233], v[38:41]
	v_mfma_f32_16x16x32_bf16 v[34:37], v[186:189], v[230:233], v[34:37]
	v_mfma_f32_16x16x32_bf16 v[22:25], v[164:167], v[238:241], v[22:25]
	v_mfma_f32_16x16x32_bf16 v[18:21], v[186:189], v[238:241], v[18:21]
	v_mfma_f32_16x16x32_bf16 v[62:65], v[168:171], v[218:221], v[62:65]
	v_mfma_f32_16x16x32_bf16 v[58:61], v[190:193], v[218:221], v[58:61]
	v_mfma_f32_16x16x32_bf16 v[54:57], v[168:171], v[226:229], v[54:57]
	v_mfma_f32_16x16x32_bf16 v[50:53], v[190:193], v[226:229], v[50:53]
	v_mfma_f32_16x16x32_bf16 v[38:41], v[168:171], v[234:237], v[38:41]
	v_mfma_f32_16x16x32_bf16 v[34:37], v[190:193], v[234:237], v[34:37]
	v_mfma_f32_16x16x32_bf16 v[22:25], v[168:171], v[242:245], v[22:25]
	v_mfma_f32_16x16x32_bf16 v[18:21], v[190:193], v[242:245], v[18:21]
	v_mfma_f32_16x16x32_bf16 v[46:49], v[198:201], v[214:217], v[46:49]
	v_mfma_f32_16x16x32_bf16 v[42:45], v[206:209], v[214:217], v[42:45]
	v_mfma_f32_16x16x32_bf16 v[30:33], v[198:201], v[222:225], v[30:33]
	v_mfma_f32_16x16x32_bf16 v[26:29], v[206:209], v[222:225], v[26:29]
	v_mfma_f32_16x16x32_bf16 v[14:17], v[198:201], v[230:233], v[14:17]
	v_mfma_f32_16x16x32_bf16 v[10:13], v[206:209], v[230:233], v[10:13]
	v_mfma_f32_16x16x32_bf16 v[6:9], v[198:201], v[238:241], v[6:9]
	v_mfma_f32_16x16x32_bf16 v[2:5], v[206:209], v[238:241], v[2:5]
	v_mfma_f32_16x16x32_bf16 v[46:49], v[202:205], v[218:221], v[46:49]
	v_mfma_f32_16x16x32_bf16 v[42:45], v[210:213], v[218:221], v[42:45]
	v_mfma_f32_16x16x32_bf16 v[30:33], v[202:205], v[226:229], v[30:33]
	v_mfma_f32_16x16x32_bf16 v[26:29], v[210:213], v[226:229], v[26:29]
	v_mfma_f32_16x16x32_bf16 v[14:17], v[202:205], v[234:237], v[14:17]
	v_mfma_f32_16x16x32_bf16 v[10:13], v[210:213], v[234:237], v[10:13]
	v_mfma_f32_16x16x32_bf16 v[6:9], v[202:205], v[242:245], v[6:9]
	v_mfma_f32_16x16x32_bf16 v[2:5], v[210:213], v[242:245], v[2:5]
	s_barrier
; #define PG8_STAGE(bufoff, gbase, voff) do { _Pragma("unroll") for (int _i = 0; _i < 2; ++_i) \
;         __builtin_amdgcn_global_load_lds((const unsigned*)((const char*)(gbase) + (voff)[_i]), (PG8_LAS unsigned*)(lds + (bufoff) + ldsw + _i * 8192), 16, 0, 0); } while (0)
; #define PG8_LDA(dst, b, h) do { _Pragma("unroll") for (int m = 0; m < 4; ++m) _Pragma("unroll") for (int k = 0; k < 2; ++k) dst[m][k] = *(const PG8_LAS bf16x8*)(lds + PG8_SA(b, h) + aoff + m * 2048 + k * 1024); } while (0)
; #define PG8_LDB(dst, b, h) do { _Pragma("unroll") for (int n = 0; n < 2; ++n) _Pragma("unroll") for (int k = 0; k < 2; ++k) dst[n][k] = *(const PG8_LAS bf16x8*)(lds + PG8_SB(b, h) + boff + n * 2048 + k * 1024); } while (0)
; #define PG8_MMA(ai, bj, At, Bt) do { __builtin_amdgcn_s_setprio(1); _Pragma("unroll") for (int m = 0; m < 4; ++m) _Pragma("unroll") for (int n = 0; n < 2; ++n) _Pragma("unroll") for (int k = 0; k < 2; ++k) \
;         acc[ai][bj][m][n] = __builtin_amdgcn_mfma_f32_16x16x32_bf16(Bt[n][k], At[m][k], acc[ai][bj][m][n], 0, 0, 0); __builtin_amdgcn_s_setprio(0); } while (0)
; #define PG8_WAIT_V(n) asm volatile("s_waitcnt vmcnt(" #n ")" ::: "memory")
; #define PG8_WAIT_L(n) asm volatile("s_waitcnt lgkmcnt(" #n ")" ::: "memory")
; #define PG8_BAR __builtin_amdgcn_s_barrier()
; #define PG8_SCHED __builtin_amdgcn_sched_barrier(0)
; template <class Epi, class Sched, bool ALIGN_EPI = false, bool SP2 = false>
; __device__ __forceinline__ void gemm_phase(PG8_LAS unsigned char* lds, const Gemm g, const Sched& S, const Epi& E) {
;     ...
;             PG8_LDB(B0, 1, 0); PG8_LDB(B1, 1, 1); PG8_SCHED; PG8_LDA(At, 1, 0); PG8_STAGE(PG8_SA(0, 1), a2 + hstepA, voffA);
;             PG8_WAIT_V(8); PG8_WAIT_L(0); PG8_BAR; PG8_MMA(0, 0, At, B0); PG8_MMA(0, 1, At, B1); PG8_BAR; PG8_SCHED;
	s_add_i32 s69, 0, 0x18000
	v_add_u32_e32 v132, s69, v161
	s_add_i32 s81, 0, 0x1c000
	ds_read_b128 v[164:167], v132
	ds_read_b128 v[168:171], v132 offset:1024
	ds_read_b128 v[186:189], v132 offset:2048
	ds_read_b128 v[190:193], v132 offset:3072
	v_add_u32_e32 v132, s81, v161
	ds_read_b128 v[198:201], v132
	ds_read_b128 v[202:205], v132 offset:1024
	ds_read_b128 v[206:209], v132 offset:2048
	ds_read_b128 v[210:213], v132 offset:3072
	s_add_u32 s10, s50, 0x40000
	s_addc_u32 s11, s51, 0
	s_mov_b32 m0, s31
	v_lshl_add_u64 v[132:133], s[10:11], 0, v[154:155]
	ds_read_b128 v[214:217], v163 offset:32768
	ds_read_b128 v[218:221], v163 offset:33792
	ds_read_b128 v[222:225], v163 offset:34816
	ds_read_b128 v[226:229], v163 offset:35840
	ds_read_b128 v[230:233], v163 offset:36864
	ds_read_b128 v[234:237], v163 offset:37888
	ds_read_b128 v[238:241], v163 offset:38912
	ds_read_b128 v[242:245], v163 offset:39936
	global_load_lds_dwordx4 v[132:133], off
	v_lshl_add_u64 v[132:133], s[10:11], 0, v[152:153]
	s_mov_b32 m0, s34
	s_nop 0
	global_load_lds_dwordx4 v[132:133], off
	s_waitcnt vmcnt(8)
	s_waitcnt lgkmcnt(0)
	s_barrier
	s_waitcnt lgkmcnt(0)
	v_mfma_f32_16x16x32_bf16 v[126:129], v[164:167], v[214:217], v[126:129]
	v_mfma_f32_16x16x32_bf16 v[122:125], v[186:189], v[214:217], v[122:125]
	v_mfma_f32_16x16x32_bf16 v[118:121], v[164:167], v[222:225], v[118:121]
	v_mfma_f32_16x16x32_bf16 v[114:117], v[186:189], v[222:225], v[114:117]
	v_mfma_f32_16x16x32_bf16 v[102:105], v[164:167], v[230:233], v[102:105]
	v_mfma_f32_16x16x32_bf16 v[98:101], v[186:189], v[230:233], v[98:101]
	v_mfma_f32_16x16x32_bf16 v[86:89], v[164:167], v[238:241], v[86:89]
	v_mfma_f32_16x16x32_bf16 v[82:85], v[186:189], v[238:241], v[82:85]
	v_mfma_f32_16x16x32_bf16 v[126:129], v[168:171], v[218:221], v[126:129]
	v_mfma_f32_16x16x32_bf16 v[122:125], v[190:193], v[218:221], v[122:125]
	v_mfma_f32_16x16x32_bf16 v[118:121], v[168:171], v[226:229], v[118:121]
	v_mfma_f32_16x16x32_bf16 v[114:117], v[190:193], v[226:229], v[114:117]
	v_mfma_f32_16x16x32_bf16 v[102:105], v[168:171], v[234:237], v[102:105]
	v_mfma_f32_16x16x32_bf16 v[98:101], v[190:193], v[234:237], v[98:101]
	v_mfma_f32_16x16x32_bf16 v[86:89], v[168:171], v[242:245], v[86:89]
	v_mfma_f32_16x16x32_bf16 v[82:85], v[190:193], v[242:245], v[82:85]
	v_mfma_f32_16x16x32_bf16 v[110:113], v[198:201], v[214:217], v[110:113]
	v_mfma_f32_16x16x32_bf16 v[106:109], v[206:209], v[214:217], v[106:109]
	v_mfma_f32_16x16x32_bf16 v[94:97], v[198:201], v[222:225], v[94:97]
	v_mfma_f32_16x16x32_bf16 v[90:93], v[206:209], v[222:225], v[90:93]
	v_mfma_f32_16x16x32_bf16 v[78:81], v[198:201], v[230:233], v[78:81]
	v_mfma_f32_16x16x32_bf16 v[74:77], v[206:209], v[230:233], v[74:77]
	v_mfma_f32_16x16x32_bf16 v[70:73], v[198:201], v[238:241], v[70:73]
	v_mfma_f32_16x16x32_bf16 v[66:69], v[206:209], v[238:241], v[66:69]
	v_mfma_f32_16x16x32_bf16 v[110:113], v[202:205], v[218:221], v[110:113]
	v_mfma_f32_16x16x32_bf16 v[106:109], v[210:213], v[218:221], v[106:109]
	v_mfma_f32_16x16x32_bf16 v[94:97], v[202:205], v[226:229], v[94:97]
	v_mfma_f32_16x16x32_bf16 v[90:93], v[210:213], v[226:229], v[90:93]
	v_mfma_f32_16x16x32_bf16 v[78:81], v[202:205], v[234:237], v[78:81]
	v_mfma_f32_16x16x32_bf16 v[74:77], v[210:213], v[234:237], v[74:77]
	v_mfma_f32_16x16x32_bf16 v[70:73], v[202:205], v[242:245], v[70:73]
	v_mfma_f32_16x16x32_bf16 v[66:69], v[210:213], v[242:245], v[66:69]
	s_barrier
; #define PG8_STAGE(bufoff, gbase, voff) do { _Pragma("unroll") for (int _i = 0; _i < 2; ++_i) \
;         __builtin_amdgcn_global_load_lds((const unsigned*)((const char*)(gbase) + (voff)[_i]), (PG8_LAS unsigned*)(lds + (bufoff) + ldsw + _i * 8192), 16, 0, 0); } while (0)
; #define PG8_LDA(dst, b, h) do { _Pragma("unroll") for (int m = 0; m < 4; ++m) _Pragma("unroll") for (int k = 0; k < 2; ++k) dst[m][k] = *(const PG8_LAS bf16x8*)(lds + PG8_SA(b, h) + aoff + m * 2048 + k * 1024); } while (0)
; #define PG8_MMA(ai, bj, At, Bt) do { __builtin_amdgcn_s_setprio(1); _Pragma("unroll") for (int m = 0; m < 4; ++m) _Pragma("unroll") for (int n = 0; n < 2; ++n) _Pragma("unroll") for (int k = 0; k < 2; ++k) \
;         acc[ai][bj][m][n] = __builtin_amdgcn_mfma_f32_16x16x32_bf16(Bt[n][k], At[m][k], acc[ai][bj][m][n], 0, 0, 0); __builtin_amdgcn_s_setprio(0); } while (0)
; #define PG8_WAIT_V(n) asm volatile("s_waitcnt vmcnt(" #n ")" ::: "memory")
; #define PG8_WAIT_L(n) asm volatile("s_waitcnt lgkmcnt(" #n ")" ::: "memory")
; #define PG8_BAR __builtin_amdgcn_s_barrier()
; #define PG8_SCHED __builtin_amdgcn_sched_barrier(0)
; template <class Epi, class Sched, bool ALIGN_EPI = false, bool SP2 = false>
; __device__ __forceinline__ void gemm_phase(PG8_LAS unsigned char* lds, const Gemm g, const Sched& S, const Epi& E) {
;     ...
;         for (int t = 0; t < nt; t += 2) {
;             const bool last = (t == nt - 2);
;             const char* a1 = cA + (size_t)(t + 1) * kstep;
;             const char* a2 = last ? nA : cA + (size_t)(t + 2) * kstep; const char* b2 = last ? nB : cB + (size_t)(t + 2) * kstep;
;             const char* a3 = a2 + kstep; const char* b3 = b2 + kstep;
;             if (last && has_next) S.a_ready(nxt);
;     ...
;             PG8_LDA(At, 1, 1); PG8_STAGE(PG8_SB(1, 0), b3, voffB); PG8_STAGE(PG8_SB(1, 1), b3 + hstepB, voffB); PG8_STAGE(PG8_SA(1, 0), a3, voffA);
;             PG8_WAIT_V(8); PG8_WAIT_L(0); PG8_BAR; PG8_MMA(1, 0, At, B0); PG8_MMA(1, 1, At, B1); PG8_BAR; PG8_SCHED;
	s_add_i32 s10, s69, s8
	v_lshl_add_u64 v[132:133], v[172:173], 0, s[2:3]
	s_mov_b32 m0, s10
	ds_read_b128 v[214:217], v163 offset:49152
	ds_read_b128 v[218:221], v163 offset:50176
	ds_read_b128 v[222:225], v163 offset:51200
	ds_read_b128 v[226:229], v163 offset:52224
	ds_read_b128 v[230:233], v163 offset:53248
	ds_read_b128 v[234:237], v163 offset:54272
	ds_read_b128 v[238:241], v163 offset:55296
	ds_read_b128 v[242:245], v163 offset:56320
	global_load_lds_dwordx4 v[132:133], off
	s_add_i32 m0, s10, 0x2000
	s_add_u32 s10, s48, 0x40080
	v_lshl_add_u64 v[132:133], v[246:247], 0, s[2:3]
	s_addc_u32 s11, s49, 0
	s_add_i32 s48, s81, s8
	global_load_lds_dwordx4 v[132:133], off
	v_lshl_add_u64 v[132:133], s[10:11], 0, v[0:1]
	s_mov_b32 m0, s48
	v_lshl_add_u64 v[130:131], v[130:131], 0, s[2:3]
	global_load_lds_dwordx4 v[132:133], off
	v_lshl_add_u64 v[132:133], s[10:11], 0, v[150:151]
	s_add_i32 m0, s48, 0x2000
	s_nop 0
	global_load_lds_dwordx4 v[132:133], off
	v_lshl_add_u64 v[132:133], v[248:249], 0, s[2:3]
	s_mov_b32 m0, s35
	s_nop 0
	global_load_lds_dwordx4 v[132:133], off
	s_mov_b32 m0, s52
	s_nop 0
	global_load_lds_dwordx4 v[130:131], off
	s_waitcnt vmcnt(8)
	s_waitcnt lgkmcnt(0)
	s_barrier
	s_waitcnt lgkmcnt(0)
	v_mfma_f32_16x16x32_bf16 v[62:65], v[164:167], v[214:217], v[62:65]
	v_mfma_f32_16x16x32_bf16 v[58:61], v[186:189], v[214:217], v[58:61]
	s_add_i32 s68, s68, 2
	v_mfma_f32_16x16x32_bf16 v[54:57], v[164:167], v[222:225], v[54:57]
	s_add_u32 s46, s46, 0x100
	v_mfma_f32_16x16x32_bf16 v[50:53], v[186:189], v[222:225], v[50:53]
	s_addc_u32 s47, s47, 0
	v_mfma_f32_16x16x32_bf16 v[38:41], v[164:167], v[230:233], v[38:41]
	s_add_u32 s62, s62, 0x100
	v_mfma_f32_16x16x32_bf16 v[34:37], v[186:189], v[230:233], v[34:37]
	s_addc_u32 s63, s63, 0
	v_mfma_f32_16x16x32_bf16 v[22:25], v[164:167], v[238:241], v[22:25]
	s_add_u32 s10, s46, 0xfffc0080
	v_mfma_f32_16x16x32_bf16 v[18:21], v[186:189], v[238:241], v[18:21]
	s_addc_u32 s11, s47, -1
	v_mfma_f32_16x16x32_bf16 v[62:65], v[168:171], v[218:221], v[62:65]
	s_add_i32 s69, 0, 0x10000
	v_mfma_f32_16x16x32_bf16 v[58:61], v[190:193], v[218:221], v[58:61]
	s_cmp_eq_u32 s68, 12
	v_mfma_f32_16x16x32_bf16 v[54:57], v[168:171], v[226:229], v[54:57]
	s_cselect_b32 s51, s41, s11
	v_mfma_f32_16x16x32_bf16 v[50:53], v[190:193], v[226:229], v[50:53]
	s_cselect_b32 s50, s57, s10
	v_mfma_f32_16x16x32_bf16 v[38:41], v[168:171], v[234:237], v[38:41]
	v_add_u32_e32 v130, s69, v161
	v_mfma_f32_16x16x32_bf16 v[34:37], v[190:193], v[234:237], v[34:37]
	s_cselect_b32 s49, s4, s63
	v_mfma_f32_16x16x32_bf16 v[22:25], v[168:171], v[242:245], v[22:25]
	s_cselect_b32 s48, s39, s62
	v_mfma_f32_16x16x32_bf16 v[18:21], v[190:193], v[242:245], v[18:21]
	s_add_i32 s81, 0, 0x14000
	v_mfma_f32_16x16x32_bf16 v[46:49], v[198:201], v[214:217], v[46:49]
	s_cmp_gt_u32 s68, 13
	v_mfma_f32_16x16x32_bf16 v[42:45], v[206:209], v[214:217], v[42:45]
	v_mfma_f32_16x16x32_bf16 v[30:33], v[198:201], v[222:225], v[30:33]
	v_mfma_f32_16x16x32_bf16 v[26:29], v[206:209], v[222:225], v[26:29]
	v_mfma_f32_16x16x32_bf16 v[14:17], v[198:201], v[230:233], v[14:17]
	v_mfma_f32_16x16x32_bf16 v[10:13], v[206:209], v[230:233], v[10:13]
	v_mfma_f32_16x16x32_bf16 v[6:9], v[198:201], v[238:241], v[6:9]
	v_mfma_f32_16x16x32_bf16 v[2:5], v[206:209], v[238:241], v[2:5]
	v_mfma_f32_16x16x32_bf16 v[46:49], v[202:205], v[218:221], v[46:49]
	v_mfma_f32_16x16x32_bf16 v[42:45], v[210:213], v[218:221], v[42:45]
	v_mfma_f32_16x16x32_bf16 v[30:33], v[202:205], v[226:229], v[30:33]
	v_mfma_f32_16x16x32_bf16 v[26:29], v[210:213], v[226:229], v[26:29]
	v_mfma_f32_16x16x32_bf16 v[14:17], v[202:205], v[234:237], v[14:17]
	v_mfma_f32_16x16x32_bf16 v[10:13], v[210:213], v[234:237], v[10:13]
	v_mfma_f32_16x16x32_bf16 v[6:9], v[202:205], v[242:245], v[6:9]
	v_mfma_f32_16x16x32_bf16 v[2:5], v[210:213], v[242:245], v[2:5]
	s_barrier
	s_cbranch_scc0 .Lgk_146
	s_and_b64 vcc, exec, s[20:21]
	s_cbranch_vccz .LBB0_149
	s_barrier

; #define PG8_STAGE(bufoff, gbase, voff) do { _Pragma("unroll") for (int _i = 0; _i < 2; ++_i) \
;         __builtin_amdgcn_global_load_lds((const unsigned*)((const char*)(gbase) + (voff)[_i]), (PG8_LAS unsigned*)(lds + (bufoff) + ldsw + _i * 8192), 16, 0, 0); } while (0)
; #define PG8_LDA(dst, b, h) do { _Pragma("unroll") for (int m = 0; m < 4; ++m) _Pragma("unroll") for (int k = 0; k < 2; ++k) dst[m][k] = *(const PG8_LAS bf16x8*)(lds + PG8_SA(b, h) + aoff + m * 2048 + k * 1024); } while (0)
; #define PG8_LDB(dst, b, h) do { _Pragma("unroll") for (int n = 0; n < 2; ++n) _Pragma("unroll") for (int k = 0; k < 2; ++k) dst[n][k] = *(const PG8_LAS bf16x8*)(lds + PG8_SB(b, h) + boff + n * 2048 + k * 1024); } while (0)
; #define PG8_MMA(ai, bj, At, Bt) do { __builtin_amdgcn_s_setprio(1); _Pragma("unroll") for (int m = 0; m < 4; ++m) _Pragma("unroll") for (int n = 0; n < 2; ++n) _Pragma("unroll") for (int k = 0; k < 2; ++k) \
;         acc[ai][bj][m][n] = __builtin_amdgcn_mfma_f32_16x16x32_bf16(Bt[n][k], At[m][k], acc[ai][bj][m][n], 0, 0, 0); __builtin_amdgcn_s_setprio(0); } while (0)
; #define PG8_WAIT_V(n) asm volatile("s_waitcnt vmcnt(" #n ")" ::: "memory")
; #define PG8_WAIT_L(n) asm volatile("s_waitcnt lgkmcnt(" #n ")" ::: "memory")
; #define PG8_BAR __builtin_amdgcn_s_barrier()
; #define PG8_SCHED __builtin_amdgcn_sched_barrier(0)
; template <class Epi, class Sched, bool ALIGN_EPI = false, bool SP2 = false>
; __device__ __forceinline__ void gemm_phase(PG8_LAS unsigned char* lds, const Gemm g, const Sched& S, const Epi& E) {
;     ...
;             PG8_LDB(B0, 0, 0); PG8_LDB(B1, 0, 1); PG8_SCHED; PG8_LDA(At, 0, 0); PG8_STAGE(PG8_SA(1, 1), a1 + hstepA, voffA);
;             PG8_WAIT_V(8); PG8_WAIT_L(0); PG8_BAR; PG8_MMA(0, 0, At, B0); PG8_MMA(0, 1, At, B1); PG8_BAR; PG8_SCHED;
;             PG8_LDA(At, 0, 1); PG8_STAGE(PG8_SB(0, 0), b2, voffB); PG8_STAGE(PG8_SB(0, 1), b2 + hstepB, voffB); PG8_STAGE(PG8_SA(0, 0), a2, voffA);
;             PG8_WAIT_V(8); PG8_WAIT_L(0); PG8_BAR; PG8_MMA(1, 0, At, B0); PG8_MMA(1, 1, At, B1); PG8_BAR; PG8_SCHED;
;             PG8_LDB(B0, 1, 0); PG8_LDB(B1, 1, 1); PG8_SCHED; PG8_LDA(At, 1, 0); PG8_STAGE(PG8_SA(0, 1), a2 + hstepA, voffA);
;             PG8_WAIT_V(8); PG8_WAIT_L(0); PG8_BAR; PG8_MMA(0, 0, At, B0); PG8_MMA(0, 1, At, B1); PG8_BAR; PG8_SCHED;
.Lgk_603:
	ds_read_b128 v[166:169], v130
	ds_read_b128 v[170:173], v130 offset:1024
	ds_read_b128 v[186:189], v130 offset:2048
	ds_read_b128 v[190:193], v130 offset:3072
	v_add_u32_e32 v130, s13, v163
	ds_read_b128 v[198:201], v130
	ds_read_b128 v[202:205], v130 offset:1024
	ds_read_b128 v[206:209], v130 offset:2048
	ds_read_b128 v[210:213], v130 offset:3072
	v_lshl_add_u64 v[130:131], s[50:51], 0, v[156:157]
	s_add_i32 m0, s31, 0xc000
	ds_read_b128 v[214:217], v165
	ds_read_b128 v[218:221], v165 offset:1024
	ds_read_b128 v[222:225], v165 offset:2048
	ds_read_b128 v[226:229], v165 offset:3072
	ds_read_b128 v[230:233], v165 offset:4096
	ds_read_b128 v[234:237], v165 offset:5120
	ds_read_b128 v[238:241], v165 offset:6144
	ds_read_b128 v[242:245], v165 offset:7168
	global_load_lds_dwordx4 v[130:131], off
	v_lshl_add_u64 v[130:131], s[50:51], 0, v[158:159]
	s_add_i32 m0, s31, 0xe000
	s_nop 0
	global_load_lds_dwordx4 v[130:131], off
	s_waitcnt vmcnt(8)
	s_waitcnt lgkmcnt(0)
	s_barrier
	s_waitcnt lgkmcnt(0)
	v_mfma_f32_16x16x32_bf16 v[126:129], v[166:169], v[214:217], v[126:129]
	v_mfma_f32_16x16x32_bf16 v[122:125], v[186:189], v[214:217], v[122:125]
	v_mfma_f32_16x16x32_bf16 v[110:113], v[166:169], v[222:225], v[110:113]
	v_mfma_f32_16x16x32_bf16 v[106:109], v[186:189], v[222:225], v[106:109]
	v_mfma_f32_16x16x32_bf16 v[94:97], v[166:169], v[230:233], v[94:97]
	v_mfma_f32_16x16x32_bf16 v[90:93], v[186:189], v[230:233], v[90:93]
	v_mfma_f32_16x16x32_bf16 v[78:81], v[166:169], v[238:241], v[78:81]
	v_mfma_f32_16x16x32_bf16 v[74:77], v[186:189], v[238:241], v[74:77]
	v_mfma_f32_16x16x32_bf16 v[126:129], v[170:173], v[218:221], v[126:129]
	v_mfma_f32_16x16x32_bf16 v[122:125], v[190:193], v[218:221], v[122:125]
	v_mfma_f32_16x16x32_bf16 v[110:113], v[170:173], v[226:229], v[110:113]
	v_mfma_f32_16x16x32_bf16 v[106:109], v[190:193], v[226:229], v[106:109]
	v_mfma_f32_16x16x32_bf16 v[94:97], v[170:173], v[234:237], v[94:97]
	v_mfma_f32_16x16x32_bf16 v[90:93], v[190:193], v[234:237], v[90:93]
	v_mfma_f32_16x16x32_bf16 v[78:81], v[170:173], v[242:245], v[78:81]
	v_mfma_f32_16x16x32_bf16 v[74:77], v[190:193], v[242:245], v[74:77]
	v_mfma_f32_16x16x32_bf16 v[118:121], v[198:201], v[214:217], v[118:121]
	v_mfma_f32_16x16x32_bf16 v[114:117], v[206:209], v[214:217], v[114:117]
	v_mfma_f32_16x16x32_bf16 v[102:105], v[198:201], v[222:225], v[102:105]
	v_mfma_f32_16x16x32_bf16 v[98:101], v[206:209], v[222:225], v[98:101]
	v_mfma_f32_16x16x32_bf16 v[86:89], v[198:201], v[230:233], v[86:89]
	v_mfma_f32_16x16x32_bf16 v[82:85], v[206:209], v[230:233], v[82:85]
	v_mfma_f32_16x16x32_bf16 v[70:73], v[198:201], v[238:241], v[70:73]
	v_mfma_f32_16x16x32_bf16 v[66:69], v[206:209], v[238:241], v[66:69]
	v_mfma_f32_16x16x32_bf16 v[118:121], v[202:205], v[218:221], v[118:121]
	v_mfma_f32_16x16x32_bf16 v[114:117], v[210:213], v[218:221], v[114:117]
	v_mfma_f32_16x16x32_bf16 v[102:105], v[202:205], v[226:229], v[102:105]
	v_mfma_f32_16x16x32_bf16 v[98:101], v[210:213], v[226:229], v[98:101]
	v_mfma_f32_16x16x32_bf16 v[86:89], v[202:205], v[234:237], v[86:89]
	v_mfma_f32_16x16x32_bf16 v[82:85], v[210:213], v[234:237], v[82:85]
	v_mfma_f32_16x16x32_bf16 v[70:73], v[202:205], v[242:245], v[70:73]
	v_mfma_f32_16x16x32_bf16 v[66:69], v[210:213], v[242:245], v[66:69]
	s_barrier
	s_add_i32 s10, s12, s30
	v_lshl_add_u64 v[130:131], s[52:53], 0, v[0:1]
	s_mov_b32 m0, s10
	ds_read_b128 v[214:217], v165 offset:16384
	ds_read_b128 v[218:221], v165 offset:17408
	ds_read_b128 v[222:225], v165 offset:18432
	ds_read_b128 v[226:229], v165 offset:19456
	ds_read_b128 v[230:233], v165 offset:20480
	ds_read_b128 v[234:237], v165 offset:21504
	ds_read_b128 v[238:241], v165 offset:22528
	ds_read_b128 v[242:245], v165 offset:23552
	global_load_lds_dwordx4 v[130:131], off
	s_add_i32 m0, s10, 0x2000
	s_add_u32 s10, s52, 0x40000
	v_lshl_add_u64 v[132:133], s[52:53], 0, v[150:151]
	s_addc_u32 s11, s53, 0
	s_add_i32 s12, s13, s30
	global_load_lds_dwordx4 v[132:133], off
	v_lshl_add_u64 v[160:161], s[10:11], 0, v[0:1]
	s_mov_b32 m0, s12
	v_lshl_add_u64 v[246:247], s[54:55], 0, v[152:153]
	global_load_lds_dwordx4 v[160:161], off
	v_lshl_add_u64 v[160:161], s[10:11], 0, v[150:151]
	s_add_i32 m0, s12, 0x2000
	s_nop 0
	global_load_lds_dwordx4 v[160:161], off
	v_lshl_add_u64 v[160:161], s[54:55], 0, v[154:155]
	s_mov_b32 m0, s31
	s_nop 0
	global_load_lds_dwordx4 v[160:161], off
	s_mov_b32 m0, s34
	s_nop 0
	global_load_lds_dwordx4 v[246:247], off
	s_waitcnt vmcnt(8)
	s_waitcnt lgkmcnt(0)
	s_barrier
	s_waitcnt lgkmcnt(0)
	v_mfma_f32_16x16x32_bf16 v[62:65], v[166:169], v[214:217], v[62:65]
	v_mfma_f32_16x16x32_bf16 v[58:61], v[186:189], v[214:217], v[58:61]
	v_mfma_f32_16x16x32_bf16 v[46:49], v[166:169], v[222:225], v[46:49]
	v_mfma_f32_16x16x32_bf16 v[42:45], v[186:189], v[222:225], v[42:45]
	v_mfma_f32_16x16x32_bf16 v[30:33], v[166:169], v[230:233], v[30:33]
	v_mfma_f32_16x16x32_bf16 v[26:29], v[186:189], v[230:233], v[26:29]
	v_mfma_f32_16x16x32_bf16 v[14:17], v[166:169], v[238:241], v[14:17]
	v_mfma_f32_16x16x32_bf16 v[10:13], v[186:189], v[238:241], v[10:13]
	v_mfma_f32_16x16x32_bf16 v[62:65], v[170:173], v[218:221], v[62:65]
	v_mfma_f32_16x16x32_bf16 v[58:61], v[190:193], v[218:221], v[58:61]
	v_mfma_f32_16x16x32_bf16 v[46:49], v[170:173], v[226:229], v[46:49]
	v_mfma_f32_16x16x32_bf16 v[42:45], v[190:193], v[226:229], v[42:45]
	v_mfma_f32_16x16x32_bf16 v[30:33], v[170:173], v[234:237], v[30:33]
	v_mfma_f32_16x16x32_bf16 v[26:29], v[190:193], v[234:237], v[26:29]
	v_mfma_f32_16x16x32_bf16 v[14:17], v[170:173], v[242:245], v[14:17]
	v_mfma_f32_16x16x32_bf16 v[10:13], v[190:193], v[242:245], v[10:13]
	v_mfma_f32_16x16x32_bf16 v[54:57], v[198:201], v[214:217], v[54:57]
	v_mfma_f32_16x16x32_bf16 v[50:53], v[206:209], v[214:217], v[50:53]
	v_mfma_f32_16x16x32_bf16 v[38:41], v[198:201], v[222:225], v[38:41]
	v_mfma_f32_16x16x32_bf16 v[34:37], v[206:209], v[222:225], v[34:37]
	v_mfma_f32_16x16x32_bf16 v[22:25], v[198:201], v[230:233], v[22:25]
	v_mfma_f32_16x16x32_bf16 v[18:21], v[206:209], v[230:233], v[18:21]
	v_mfma_f32_16x16x32_bf16 v[6:9], v[198:201], v[238:241], v[6:9]
	v_mfma_f32_16x16x32_bf16 v[2:5], v[206:209], v[238:241], v[2:5]
	v_mfma_f32_16x16x32_bf16 v[54:57], v[202:205], v[218:221], v[54:57]
	v_mfma_f32_16x16x32_bf16 v[50:53], v[210:213], v[218:221], v[50:53]
	v_mfma_f32_16x16x32_bf16 v[38:41], v[202:205], v[226:229], v[38:41]
	v_mfma_f32_16x16x32_bf16 v[34:37], v[210:213], v[226:229], v[34:37]
	v_mfma_f32_16x16x32_bf16 v[22:25], v[202:205], v[234:237], v[22:25]
	v_mfma_f32_16x16x32_bf16 v[18:21], v[210:213], v[234:237], v[18:21]
	v_mfma_f32_16x16x32_bf16 v[6:9], v[202:205], v[242:245], v[6:9]
	v_mfma_f32_16x16x32_bf16 v[2:5], v[210:213], v[242:245], v[2:5]
	s_barrier
; #define PG8_STAGE(bufoff, gbase, voff) do { _Pragma("unroll") for (int _i = 0; _i < 2; ++_i) \
;         __builtin_amdgcn_global_load_lds((const unsigned*)((const char*)(gbase) + (voff)[_i]), (PG8_LAS unsigned*)(lds + (bufoff) + ldsw + _i * 8192), 16, 0, 0); } while (0)
; #define PG8_LDA(dst, b, h) do { _Pragma("unroll") for (int m = 0; m < 4; ++m) _Pragma("unroll") for (int k = 0; k < 2; ++k) dst[m][k] = *(const PG8_LAS bf16x8*)(lds + PG8_SA(b, h) + aoff + m * 2048 + k * 1024); } while (0)
; #define PG8_LDB(dst, b, h) do { _Pragma("unroll") for (int n = 0; n < 2; ++n) _Pragma("unroll") for (int k = 0; k < 2; ++k) dst[n][k] = *(const PG8_LAS bf16x8*)(lds + PG8_SB(b, h) + boff + n * 2048 + k * 1024); } while (0)
; #define PG8_MMA(ai, bj, At, Bt) do { __builtin_amdgcn_s_setprio(1); _Pragma("unroll") for (int m = 0; m < 4; ++m) _Pragma("unroll") for (int n = 0; n < 2; ++n) _Pragma("unroll") for (int k = 0; k < 2; ++k) \
;         acc[ai][bj][m][n] = __builtin_amdgcn_mfma_f32_16x16x32_bf16(Bt[n][k], At[m][k], acc[ai][bj][m][n], 0, 0, 0); __builtin_amdgcn_s_setprio(0); } while (0)
; #define PG8_WAIT_V(n) asm volatile("s_waitcnt vmcnt(" #n ")" ::: "memory")
; #define PG8_WAIT_L(n) asm volatile("s_waitcnt lgkmcnt(" #n ")" ::: "memory")
; #define PG8_BAR __builtin_amdgcn_s_barrier()
; #define PG8_SCHED __builtin_amdgcn_sched_barrier(0)
; template <class Epi, class Sched, bool ALIGN_EPI = false, bool SP2 = false>
; __device__ __forceinline__ void gemm_phase(PG8_LAS unsigned char* lds, const Gemm g, const Sched& S, const Epi& E) {
;     ...
;             PG8_LDB(B0, 1, 0); PG8_LDB(B1, 1, 1); PG8_SCHED; PG8_LDA(At, 1, 0); PG8_STAGE(PG8_SA(0, 1), a2 + hstepA, voffA);
;             PG8_WAIT_V(8); PG8_WAIT_L(0); PG8_BAR; PG8_MMA(0, 0, At, B0); PG8_MMA(0, 1, At, B1); PG8_BAR; PG8_SCHED;
	s_add_i32 s12, 0, 0x18000
	s_add_i32 s13, 0, 0x1c000
	v_add_u32_e32 v190, s12, v163
	v_add_u32_e32 v210, s13, v163
	ds_read_b128 v[166:169], v190
	ds_read_b128 v[170:173], v190 offset:1024
	ds_read_b128 v[186:189], v190 offset:2048
	ds_read_b128 v[190:193], v190 offset:3072
	ds_read_b128 v[198:201], v210
	ds_read_b128 v[202:205], v210 offset:1024
	ds_read_b128 v[206:209], v210 offset:2048
	ds_read_b128 v[210:213], v210 offset:3072
	s_add_u32 s10, s54, 0x40000
	s_addc_u32 s11, s55, 0
	s_mov_b32 m0, s35
	v_lshl_add_u64 v[248:249], s[10:11], 0, v[154:155]
	ds_read_b128 v[214:217], v165 offset:32768
	ds_read_b128 v[218:221], v165 offset:33792
	ds_read_b128 v[222:225], v165 offset:34816
	ds_read_b128 v[226:229], v165 offset:35840
	ds_read_b128 v[230:233], v165 offset:36864
	ds_read_b128 v[234:237], v165 offset:37888
	ds_read_b128 v[238:241], v165 offset:38912
	ds_read_b128 v[242:245], v165 offset:39936
	global_load_lds_dwordx4 v[248:249], off
	v_lshl_add_u64 v[248:249], s[10:11], 0, v[152:153]
	s_mov_b32 m0, s56
	s_nop 0
	global_load_lds_dwordx4 v[248:249], off
	s_waitcnt vmcnt(8)
	s_waitcnt lgkmcnt(0)
	s_barrier
	s_waitcnt lgkmcnt(0)
	v_mfma_f32_16x16x32_bf16 v[126:129], v[166:169], v[214:217], v[126:129]
	v_mfma_f32_16x16x32_bf16 v[122:125], v[186:189], v[214:217], v[122:125]
	v_mfma_f32_16x16x32_bf16 v[110:113], v[166:169], v[222:225], v[110:113]
	v_mfma_f32_16x16x32_bf16 v[106:109], v[186:189], v[222:225], v[106:109]
	v_mfma_f32_16x16x32_bf16 v[94:97], v[166:169], v[230:233], v[94:97]
	v_mfma_f32_16x16x32_bf16 v[90:93], v[186:189], v[230:233], v[90:93]
	v_mfma_f32_16x16x32_bf16 v[78:81], v[166:169], v[238:241], v[78:81]
	v_mfma_f32_16x16x32_bf16 v[74:77], v[186:189], v[238:241], v[74:77]
	v_mfma_f32_16x16x32_bf16 v[126:129], v[170:173], v[218:221], v[126:129]
	v_mfma_f32_16x16x32_bf16 v[122:125], v[190:193], v[218:221], v[122:125]
	v_mfma_f32_16x16x32_bf16 v[110:113], v[170:173], v[226:229], v[110:113]
	v_mfma_f32_16x16x32_bf16 v[106:109], v[190:193], v[226:229], v[106:109]
	v_mfma_f32_16x16x32_bf16 v[94:97], v[170:173], v[234:237], v[94:97]
	v_mfma_f32_16x16x32_bf16 v[90:93], v[190:193], v[234:237], v[90:93]
	v_mfma_f32_16x16x32_bf16 v[78:81], v[170:173], v[242:245], v[78:81]
	v_mfma_f32_16x16x32_bf16 v[74:77], v[190:193], v[242:245], v[74:77]
	v_mfma_f32_16x16x32_bf16 v[118:121], v[198:201], v[214:217], v[118:121]
	v_mfma_f32_16x16x32_bf16 v[114:117], v[206:209], v[214:217], v[114:117]
	v_mfma_f32_16x16x32_bf16 v[102:105], v[198:201], v[222:225], v[102:105]
	v_mfma_f32_16x16x32_bf16 v[98:101], v[206:209], v[222:225], v[98:101]
	v_mfma_f32_16x16x32_bf16 v[86:89], v[198:201], v[230:233], v[86:89]
	v_mfma_f32_16x16x32_bf16 v[82:85], v[206:209], v[230:233], v[82:85]
	v_mfma_f32_16x16x32_bf16 v[70:73], v[198:201], v[238:241], v[70:73]
	v_mfma_f32_16x16x32_bf16 v[66:69], v[206:209], v[238:241], v[66:69]
	v_mfma_f32_16x16x32_bf16 v[118:121], v[202:205], v[218:221], v[118:121]
	v_mfma_f32_16x16x32_bf16 v[114:117], v[210:213], v[218:221], v[114:117]
	v_mfma_f32_16x16x32_bf16 v[102:105], v[202:205], v[226:229], v[102:105]
	v_mfma_f32_16x16x32_bf16 v[98:101], v[210:213], v[226:229], v[98:101]
	v_mfma_f32_16x16x32_bf16 v[86:89], v[202:205], v[234:237], v[86:89]
	v_mfma_f32_16x16x32_bf16 v[82:85], v[210:213], v[234:237], v[82:85]
	v_mfma_f32_16x16x32_bf16 v[70:73], v[202:205], v[242:245], v[70:73]
	v_mfma_f32_16x16x32_bf16 v[66:69], v[210:213], v[242:245], v[66:69]
	s_barrier
; #define PG8_STAGE(bufoff, gbase, voff) do { _Pragma("unroll") for (int _i = 0; _i < 2; ++_i) \
;         __builtin_amdgcn_global_load_lds((const unsigned*)((const char*)(gbase) + (voff)[_i]), (PG8_LAS unsigned*)(lds + (bufoff) + ldsw + _i * 8192), 16, 0, 0); } while (0)
; #define PG8_LDA(dst, b, h) do { _Pragma("unroll") for (int m = 0; m < 4; ++m) _Pragma("unroll") for (int k = 0; k < 2; ++k) dst[m][k] = *(const PG8_LAS bf16x8*)(lds + PG8_SA(b, h) + aoff + m * 2048 + k * 1024); } while (0)
; #define PG8_MMA(ai, bj, At, Bt) do { __builtin_amdgcn_s_setprio(1); _Pragma("unroll") for (int m = 0; m < 4; ++m) _Pragma("unroll") for (int n = 0; n < 2; ++n) _Pragma("unroll") for (int k = 0; k < 2; ++k) \
;         acc[ai][bj][m][n] = __builtin_amdgcn_mfma_f32_16x16x32_bf16(Bt[n][k], At[m][k], acc[ai][bj][m][n], 0, 0, 0); __builtin_amdgcn_s_setprio(0); } while (0)
; #define PG8_WAIT_V(n) asm volatile("s_waitcnt vmcnt(" #n ")" ::: "memory")
; #define PG8_WAIT_L(n) asm volatile("s_waitcnt lgkmcnt(" #n ")" ::: "memory")
; #define PG8_BAR __builtin_amdgcn_s_barrier()
; #define PG8_SCHED __builtin_amdgcn_sched_barrier(0)
; template <class Epi, class Sched, bool ALIGN_EPI = false, bool SP2 = false>
; __device__ __forceinline__ void gemm_phase(PG8_LAS unsigned char* lds, const Gemm g, const Sched& S, const Epi& E) {
;     ...
;         for (int t = 0; t < nt; t += 2) {
;             const bool last = (t == nt - 2);
;             const char* a1 = cA + (size_t)(t + 1) * kstep;
;             const char* a2 = last ? nA : cA + (size_t)(t + 2) * kstep; const char* b2 = last ? nB : cB + (size_t)(t + 2) * kstep;
;             const char* a3 = a2 + kstep; const char* b3 = b2 + kstep;
;             if (last && has_next) S.a_ready(nxt);
;     ...
;             PG8_LDA(At, 1, 1); PG8_STAGE(PG8_SB(1, 0), b3, voffB); PG8_STAGE(PG8_SB(1, 1), b3 + hstepB, voffB); PG8_STAGE(PG8_SA(1, 0), a3, voffA);
;             PG8_WAIT_V(8); PG8_WAIT_L(0); PG8_BAR; PG8_MMA(1, 0, At, B0); PG8_MMA(1, 1, At, B1); PG8_BAR; PG8_SCHED;
	s_add_i32 s10, s12, s30
	v_lshl_add_u64 v[130:131], v[130:131], 0, s[2:3]
	s_mov_b32 m0, s10
	ds_read_b128 v[214:217], v165 offset:49152
	ds_read_b128 v[218:221], v165 offset:50176
	ds_read_b128 v[222:225], v165 offset:51200
	ds_read_b128 v[226:229], v165 offset:52224
	ds_read_b128 v[230:233], v165 offset:53248
	ds_read_b128 v[234:237], v165 offset:54272
	ds_read_b128 v[238:241], v165 offset:55296
	ds_read_b128 v[242:245], v165 offset:56320
	global_load_lds_dwordx4 v[130:131], off
	s_add_i32 m0, s10, 0x2000
	s_add_u32 s10, s52, 0x40080
	v_lshl_add_u64 v[130:131], v[132:133], 0, s[2:3]
	s_addc_u32 s11, s53, 0
	s_add_i32 s12, s13, s30
	global_load_lds_dwordx4 v[130:131], off
	v_lshl_add_u64 v[130:131], s[10:11], 0, v[0:1]
	s_mov_b32 m0, s12
	s_nop 0
	global_load_lds_dwordx4 v[130:131], off
	v_lshl_add_u64 v[130:131], s[10:11], 0, v[150:151]
	s_add_i32 m0, s12, 0x2000
	s_nop 0
	global_load_lds_dwordx4 v[130:131], off
	v_lshl_add_u64 v[130:131], v[160:161], 0, s[2:3]
	s_mov_b32 m0, s57
	s_nop 0
	global_load_lds_dwordx4 v[130:131], off
	v_lshl_add_u64 v[130:131], v[246:247], 0, s[2:3]
	s_mov_b32 m0, s62
	s_nop 0
	global_load_lds_dwordx4 v[130:131], off
	s_waitcnt vmcnt(8)
	s_waitcnt lgkmcnt(0)
	s_barrier
	s_waitcnt lgkmcnt(0)
	v_mfma_f32_16x16x32_bf16 v[62:65], v[166:169], v[214:217], v[62:65]
	v_mfma_f32_16x16x32_bf16 v[58:61], v[186:189], v[214:217], v[58:61]
	s_add_i32 s95, s95, 2
	v_mfma_f32_16x16x32_bf16 v[46:49], v[166:169], v[222:225], v[46:49]
	s_add_u32 s50, s50, 0x100
	v_mfma_f32_16x16x32_bf16 v[42:45], v[186:189], v[222:225], v[42:45]
	s_addc_u32 s51, s51, 0
	v_mfma_f32_16x16x32_bf16 v[30:33], v[166:169], v[230:233], v[30:33]
	s_add_u32 s91, s91, 0x100
	v_mfma_f32_16x16x32_bf16 v[26:29], v[186:189], v[230:233], v[26:29]
	s_addc_u32 s94, s94, 0
	v_mfma_f32_16x16x32_bf16 v[14:17], v[166:169], v[238:241], v[14:17]
	s_add_u32 s10, s50, 0xfffc0080
	v_mfma_f32_16x16x32_bf16 v[10:13], v[186:189], v[238:241], v[10:13]
	s_addc_u32 s11, s51, -1
	v_mfma_f32_16x16x32_bf16 v[62:65], v[170:173], v[218:221], v[62:65]
	s_add_i32 s12, 0, 0x10000
	v_mfma_f32_16x16x32_bf16 v[58:61], v[190:193], v[218:221], v[58:61]
	s_cmp_eq_u32 s95, 12
	v_mfma_f32_16x16x32_bf16 v[46:49], v[170:173], v[226:229], v[46:49]
	s_cselect_b32 s55, s45, s11
	v_mfma_f32_16x16x32_bf16 v[42:45], v[190:193], v[226:229], v[42:45]
	s_cselect_b32 s54, s90, s10
	v_mfma_f32_16x16x32_bf16 v[30:33], v[170:173], v[234:237], v[30:33]
	v_add_u32_e32 v130, s12, v163
	v_mfma_f32_16x16x32_bf16 v[26:29], v[190:193], v[234:237], v[26:29]
	s_cselect_b32 s53, s4, s94
	v_mfma_f32_16x16x32_bf16 v[14:17], v[170:173], v[242:245], v[14:17]
	s_cselect_b32 s52, s43, s91
	v_mfma_f32_16x16x32_bf16 v[10:13], v[190:193], v[242:245], v[10:13]
	s_add_i32 s13, 0, 0x14000
	v_mfma_f32_16x16x32_bf16 v[54:57], v[198:201], v[214:217], v[54:57]
	s_cmp_gt_u32 s95, 13
	v_mfma_f32_16x16x32_bf16 v[50:53], v[206:209], v[214:217], v[50:53]
	v_mfma_f32_16x16x32_bf16 v[38:41], v[198:201], v[222:225], v[38:41]
	v_mfma_f32_16x16x32_bf16 v[34:37], v[206:209], v[222:225], v[34:37]
	v_mfma_f32_16x16x32_bf16 v[22:25], v[198:201], v[230:233], v[22:25]
	v_mfma_f32_16x16x32_bf16 v[18:21], v[206:209], v[230:233], v[18:21]
	v_mfma_f32_16x16x32_bf16 v[6:9], v[198:201], v[238:241], v[6:9]
	v_mfma_f32_16x16x32_bf16 v[2:5], v[206:209], v[238:241], v[2:5]
	v_mfma_f32_16x16x32_bf16 v[54:57], v[202:205], v[218:221], v[54:57]
	v_mfma_f32_16x16x32_bf16 v[50:53], v[210:213], v[218:221], v[50:53]
	v_mfma_f32_16x16x32_bf16 v[38:41], v[202:205], v[226:229], v[38:41]
	v_mfma_f32_16x16x32_bf16 v[34:37], v[210:213], v[226:229], v[34:37]
	v_mfma_f32_16x16x32_bf16 v[22:25], v[202:205], v[234:237], v[22:25]
	v_mfma_f32_16x16x32_bf16 v[18:21], v[210:213], v[234:237], v[18:21]
	v_mfma_f32_16x16x32_bf16 v[6:9], v[202:205], v[242:245], v[6:9]
	v_mfma_f32_16x16x32_bf16 v[2:5], v[210:213], v[242:245], v[2:5]
	s_barrier
	s_cbranch_scc0 .Lgk_603
	s_and_b64 vcc, exec, s[40:41]
	s_cbranch_vccz .LBB0_606
	s_barrier

; #define PG8_STAGE(bufoff, gbase, voff) do { _Pragma("unroll") for (int _i = 0; _i < 2; ++_i) \
;         __builtin_amdgcn_global_load_lds((const unsigned*)((const char*)(gbase) + (voff)[_i]), (PG8_LAS unsigned*)(lds + (bufoff) + ldsw + _i * 8192), 16, 0, 0); } while (0)
; #define PG8_LDA(dst, b, h) do { _Pragma("unroll") for (int m = 0; m < 4; ++m) _Pragma("unroll") for (int k = 0; k < 2; ++k) dst[m][k] = *(const PG8_LAS bf16x8*)(lds + PG8_SA(b, h) + aoff + m * 2048 + k * 1024); } while (0)
; #define PG8_LDB(dst, b, h) do { _Pragma("unroll") for (int n = 0; n < 2; ++n) _Pragma("unroll") for (int k = 0; k < 2; ++k) dst[n][k] = *(const PG8_LAS bf16x8*)(lds + PG8_SB(b, h) + boff + n * 2048 + k * 1024); } while (0)
; #define PG8_MMA(ai, bj, At, Bt) do { __builtin_amdgcn_s_setprio(1); _Pragma("unroll") for (int m = 0; m < 4; ++m) _Pragma("unroll") for (int n = 0; n < 2; ++n) _Pragma("unroll") for (int k = 0; k < 2; ++k) \
;         acc[ai][bj][m][n] = __builtin_amdgcn_mfma_f32_16x16x32_bf16(Bt[n][k], At[m][k], acc[ai][bj][m][n], 0, 0, 0); __builtin_amdgcn_s_setprio(0); } while (0)
; #define PG8_WAIT_V(n) asm volatile("s_waitcnt vmcnt(" #n ")" ::: "memory")
; #define PG8_WAIT_L(n) asm volatile("s_waitcnt lgkmcnt(" #n ")" ::: "memory")
; #define PG8_BAR __builtin_amdgcn_s_barrier()
; #define PG8_SCHED __builtin_amdgcn_sched_barrier(0)
; template <class Epi, class Sched, bool ALIGN_EPI = false, bool SP2 = false>
; __device__ __forceinline__ void gemm_phase(PG8_LAS unsigned char* lds, const Gemm g, const Sched& S, const Epi& E) {
;     ...
;             PG8_LDB(B0, 0, 0); PG8_LDB(B1, 0, 1); PG8_SCHED; PG8_LDA(At, 0, 0); PG8_STAGE(PG8_SA(1, 1), a1 + hstepA, voffA);
;             PG8_WAIT_V(8); PG8_WAIT_L(0); PG8_BAR; PG8_MMA(0, 0, At, B0); PG8_MMA(0, 1, At, B1); PG8_BAR; PG8_SCHED;
;             PG8_LDA(At, 0, 1); PG8_STAGE(PG8_SB(0, 0), b2, voffB); PG8_STAGE(PG8_SB(0, 1), b2 + hstepB, voffB); PG8_STAGE(PG8_SA(0, 0), a2, voffA);
;             PG8_WAIT_V(8); PG8_WAIT_L(0); PG8_BAR; PG8_MMA(1, 0, At, B0); PG8_MMA(1, 1, At, B1); PG8_BAR; PG8_SCHED;
;             PG8_LDB(B0, 1, 0); PG8_LDB(B1, 1, 1); PG8_SCHED; PG8_LDA(At, 1, 0); PG8_STAGE(PG8_SA(0, 1), a2 + hstepA, voffA);
;             PG8_WAIT_V(8); PG8_WAIT_L(0); PG8_BAR; PG8_MMA(0, 0, At, B0); PG8_MMA(0, 1, At, B1); PG8_BAR; PG8_SCHED;
.Lgk_623:
	ds_read_b128 v[160:163], v130
	ds_read_b128 v[164:167], v130 offset:1024
	ds_read_b128 v[186:189], v130 offset:2048
	ds_read_b128 v[190:193], v130 offset:3072
	v_add_u32_e32 v130, s13, v169
	ds_read_b128 v[198:201], v130
	ds_read_b128 v[202:205], v130 offset:1024
	ds_read_b128 v[206:209], v130 offset:2048
	ds_read_b128 v[210:213], v130 offset:3072
	v_lshl_add_u64 v[130:131], s[54:55], 0, v[156:157]
	s_add_i32 m0, s53, 0xc000
	ds_read_b128 v[214:217], v171
	ds_read_b128 v[218:221], v171 offset:1024
	ds_read_b128 v[222:225], v171 offset:2048
	ds_read_b128 v[226:229], v171 offset:3072
	ds_read_b128 v[230:233], v171 offset:4096
	ds_read_b128 v[234:237], v171 offset:5120
	ds_read_b128 v[238:241], v171 offset:6144
	ds_read_b128 v[242:245], v171 offset:7168
	global_load_lds_dwordx4 v[130:131], off
	v_lshl_add_u64 v[130:131], s[54:55], 0, v[158:159]
	s_add_i32 m0, s53, 0xe000
	s_nop 0
	global_load_lds_dwordx4 v[130:131], off
	s_waitcnt vmcnt(8)
	s_waitcnt lgkmcnt(0)
	s_barrier
	s_waitcnt lgkmcnt(0)
	v_mfma_f32_16x16x32_bf16 v[126:129], v[160:163], v[214:217], v[126:129]
	v_mfma_f32_16x16x32_bf16 v[122:125], v[186:189], v[214:217], v[122:125]
	v_mfma_f32_16x16x32_bf16 v[110:113], v[160:163], v[222:225], v[110:113]
	v_mfma_f32_16x16x32_bf16 v[106:109], v[186:189], v[222:225], v[106:109]
	v_mfma_f32_16x16x32_bf16 v[94:97], v[160:163], v[230:233], v[94:97]
	v_mfma_f32_16x16x32_bf16 v[90:93], v[186:189], v[230:233], v[90:93]
	v_mfma_f32_16x16x32_bf16 v[78:81], v[160:163], v[238:241], v[78:81]
	v_mfma_f32_16x16x32_bf16 v[74:77], v[186:189], v[238:241], v[74:77]
	v_mfma_f32_16x16x32_bf16 v[126:129], v[164:167], v[218:221], v[126:129]
	v_mfma_f32_16x16x32_bf16 v[122:125], v[190:193], v[218:221], v[122:125]
	v_mfma_f32_16x16x32_bf16 v[110:113], v[164:167], v[226:229], v[110:113]
	v_mfma_f32_16x16x32_bf16 v[106:109], v[190:193], v[226:229], v[106:109]
	v_mfma_f32_16x16x32_bf16 v[94:97], v[164:167], v[234:237], v[94:97]
	v_mfma_f32_16x16x32_bf16 v[90:93], v[190:193], v[234:237], v[90:93]
	v_mfma_f32_16x16x32_bf16 v[78:81], v[164:167], v[242:245], v[78:81]
	v_mfma_f32_16x16x32_bf16 v[74:77], v[190:193], v[242:245], v[74:77]
	v_mfma_f32_16x16x32_bf16 v[118:121], v[198:201], v[214:217], v[118:121]
	v_mfma_f32_16x16x32_bf16 v[114:117], v[206:209], v[214:217], v[114:117]
	v_mfma_f32_16x16x32_bf16 v[102:105], v[198:201], v[222:225], v[102:105]
	v_mfma_f32_16x16x32_bf16 v[98:101], v[206:209], v[222:225], v[98:101]
	v_mfma_f32_16x16x32_bf16 v[86:89], v[198:201], v[230:233], v[86:89]
	v_mfma_f32_16x16x32_bf16 v[82:85], v[206:209], v[230:233], v[82:85]
	v_mfma_f32_16x16x32_bf16 v[70:73], v[198:201], v[238:241], v[70:73]
	v_mfma_f32_16x16x32_bf16 v[66:69], v[206:209], v[238:241], v[66:69]
	v_mfma_f32_16x16x32_bf16 v[118:121], v[202:205], v[218:221], v[118:121]
	v_mfma_f32_16x16x32_bf16 v[114:117], v[210:213], v[218:221], v[114:117]
	v_mfma_f32_16x16x32_bf16 v[102:105], v[202:205], v[226:229], v[102:105]
	v_mfma_f32_16x16x32_bf16 v[98:101], v[210:213], v[226:229], v[98:101]
	v_mfma_f32_16x16x32_bf16 v[86:89], v[202:205], v[234:237], v[86:89]
	v_mfma_f32_16x16x32_bf16 v[82:85], v[210:213], v[234:237], v[82:85]
	v_mfma_f32_16x16x32_bf16 v[70:73], v[202:205], v[242:245], v[70:73]
	v_mfma_f32_16x16x32_bf16 v[66:69], v[210:213], v[242:245], v[66:69]
	s_barrier
	s_add_i32 s10, s12, s68
	v_lshl_add_u64 v[130:131], s[56:57], 0, v[0:1]
	s_mov_b32 m0, s10
	ds_read_b128 v[214:217], v171 offset:16384
	ds_read_b128 v[218:221], v171 offset:17408
	ds_read_b128 v[222:225], v171 offset:18432
	ds_read_b128 v[226:229], v171 offset:19456
	ds_read_b128 v[230:233], v171 offset:20480
	ds_read_b128 v[234:237], v171 offset:21504
	ds_read_b128 v[238:241], v171 offset:22528
	ds_read_b128 v[242:245], v171 offset:23552
	global_load_lds_dwordx4 v[130:131], off
	s_add_i32 m0, s10, 0x2000
	s_add_u32 s10, s56, 0x20000
	v_lshl_add_u64 v[132:133], s[56:57], 0, v[150:151]
	s_addc_u32 s11, s57, 0
	s_add_i32 s12, s13, s68
	global_load_lds_dwordx4 v[132:133], off
	v_lshl_add_u64 v[172:173], s[10:11], 0, v[0:1]
	s_mov_b32 m0, s12
	v_lshl_add_u64 v[246:247], s[62:63], 0, v[152:153]
	global_load_lds_dwordx4 v[172:173], off
	v_lshl_add_u64 v[172:173], s[10:11], 0, v[150:151]
	s_add_i32 m0, s12, 0x2000
	s_nop 0
	global_load_lds_dwordx4 v[172:173], off
	v_lshl_add_u64 v[172:173], s[62:63], 0, v[154:155]
	s_mov_b32 m0, s53
	s_nop 0
	global_load_lds_dwordx4 v[172:173], off
	s_mov_b32 m0, s69
	s_nop 0
	global_load_lds_dwordx4 v[246:247], off
	s_waitcnt vmcnt(8)
	s_waitcnt lgkmcnt(0)
	s_barrier
	s_waitcnt lgkmcnt(0)
	v_mfma_f32_16x16x32_bf16 v[62:65], v[160:163], v[214:217], v[62:65]
	v_mfma_f32_16x16x32_bf16 v[58:61], v[186:189], v[214:217], v[58:61]
	v_mfma_f32_16x16x32_bf16 v[46:49], v[160:163], v[222:225], v[46:49]
	v_mfma_f32_16x16x32_bf16 v[42:45], v[186:189], v[222:225], v[42:45]
	v_mfma_f32_16x16x32_bf16 v[30:33], v[160:163], v[230:233], v[30:33]
	v_mfma_f32_16x16x32_bf16 v[26:29], v[186:189], v[230:233], v[26:29]
	v_mfma_f32_16x16x32_bf16 v[14:17], v[160:163], v[238:241], v[14:17]
	v_mfma_f32_16x16x32_bf16 v[10:13], v[186:189], v[238:241], v[10:13]
	v_mfma_f32_16x16x32_bf16 v[62:65], v[164:167], v[218:221], v[62:65]
	v_mfma_f32_16x16x32_bf16 v[58:61], v[190:193], v[218:221], v[58:61]
	v_mfma_f32_16x16x32_bf16 v[46:49], v[164:167], v[226:229], v[46:49]
	v_mfma_f32_16x16x32_bf16 v[42:45], v[190:193], v[226:229], v[42:45]
	v_mfma_f32_16x16x32_bf16 v[30:33], v[164:167], v[234:237], v[30:33]
	v_mfma_f32_16x16x32_bf16 v[26:29], v[190:193], v[234:237], v[26:29]
	v_mfma_f32_16x16x32_bf16 v[14:17], v[164:167], v[242:245], v[14:17]
	v_mfma_f32_16x16x32_bf16 v[10:13], v[190:193], v[242:245], v[10:13]
	v_mfma_f32_16x16x32_bf16 v[54:57], v[198:201], v[214:217], v[54:57]
	v_mfma_f32_16x16x32_bf16 v[50:53], v[206:209], v[214:217], v[50:53]
	v_mfma_f32_16x16x32_bf16 v[38:41], v[198:201], v[222:225], v[38:41]
	v_mfma_f32_16x16x32_bf16 v[34:37], v[206:209], v[222:225], v[34:37]
	v_mfma_f32_16x16x32_bf16 v[22:25], v[198:201], v[230:233], v[22:25]
	v_mfma_f32_16x16x32_bf16 v[18:21], v[206:209], v[230:233], v[18:21]
	v_mfma_f32_16x16x32_bf16 v[6:9], v[198:201], v[238:241], v[6:9]
	v_mfma_f32_16x16x32_bf16 v[2:5], v[206:209], v[238:241], v[2:5]
	v_mfma_f32_16x16x32_bf16 v[54:57], v[202:205], v[218:221], v[54:57]
	v_mfma_f32_16x16x32_bf16 v[50:53], v[210:213], v[218:221], v[50:53]
	v_mfma_f32_16x16x32_bf16 v[38:41], v[202:205], v[226:229], v[38:41]
	v_mfma_f32_16x16x32_bf16 v[34:37], v[210:213], v[226:229], v[34:37]
	v_mfma_f32_16x16x32_bf16 v[22:25], v[202:205], v[234:237], v[22:25]
	v_mfma_f32_16x16x32_bf16 v[18:21], v[210:213], v[234:237], v[18:21]
	v_mfma_f32_16x16x32_bf16 v[6:9], v[202:205], v[242:245], v[6:9]
	v_mfma_f32_16x16x32_bf16 v[2:5], v[210:213], v[242:245], v[2:5]
	s_barrier
; #define PG8_STAGE(bufoff, gbase, voff) do { _Pragma("unroll") for (int _i = 0; _i < 2; ++_i) \
;         __builtin_amdgcn_global_load_lds((const unsigned*)((const char*)(gbase) + (voff)[_i]), (PG8_LAS unsigned*)(lds + (bufoff) + ldsw + _i * 8192), 16, 0, 0); } while (0)
; #define PG8_LDA(dst, b, h) do { _Pragma("unroll") for (int m = 0; m < 4; ++m) _Pragma("unroll") for (int k = 0; k < 2; ++k) dst[m][k] = *(const PG8_LAS bf16x8*)(lds + PG8_SA(b, h) + aoff + m * 2048 + k * 1024); } while (0)
; #define PG8_LDB(dst, b, h) do { _Pragma("unroll") for (int n = 0; n < 2; ++n) _Pragma("unroll") for (int k = 0; k < 2; ++k) dst[n][k] = *(const PG8_LAS bf16x8*)(lds + PG8_SB(b, h) + boff + n * 2048 + k * 1024); } while (0)
; #define PG8_MMA(ai, bj, At, Bt) do { __builtin_amdgcn_s_setprio(1); _Pragma("unroll") for (int m = 0; m < 4; ++m) _Pragma("unroll") for (int n = 0; n < 2; ++n) _Pragma("unroll") for (int k = 0; k < 2; ++k) \
;         acc[ai][bj][m][n] = __builtin_amdgcn_mfma_f32_16x16x32_bf16(Bt[n][k], At[m][k], acc[ai][bj][m][n], 0, 0, 0); __builtin_amdgcn_s_setprio(0); } while (0)
; #define PG8_WAIT_V(n) asm volatile("s_waitcnt vmcnt(" #n ")" ::: "memory")
; #define PG8_WAIT_L(n) asm volatile("s_waitcnt lgkmcnt(" #n ")" ::: "memory")
; #define PG8_BAR __builtin_amdgcn_s_barrier()
; #define PG8_SCHED __builtin_amdgcn_sched_barrier(0)
; template <class Epi, class Sched, bool ALIGN_EPI = false, bool SP2 = false>
; __device__ __forceinline__ void gemm_phase(PG8_LAS unsigned char* lds, const Gemm g, const Sched& S, const Epi& E) {
;     ...
;             PG8_LDB(B0, 1, 0); PG8_LDB(B1, 1, 1); PG8_SCHED; PG8_LDA(At, 1, 0); PG8_STAGE(PG8_SA(0, 1), a2 + hstepA, voffA);
;             PG8_WAIT_V(8); PG8_WAIT_L(0); PG8_BAR; PG8_MMA(0, 0, At, B0); PG8_MMA(0, 1, At, B1); PG8_BAR; PG8_SCHED;
	s_add_i32 s12, 0, 0x18000
	s_add_i32 s13, 0, 0x1c000
	v_add_u32_e32 v190, s12, v169
	v_add_u32_e32 v210, s13, v169
	ds_read_b128 v[160:163], v190
	ds_read_b128 v[164:167], v190 offset:1024
	ds_read_b128 v[186:189], v190 offset:2048
	ds_read_b128 v[190:193], v190 offset:3072
	ds_read_b128 v[198:201], v210
	ds_read_b128 v[202:205], v210 offset:1024
	ds_read_b128 v[206:209], v210 offset:2048
	ds_read_b128 v[210:213], v210 offset:3072
	s_add_u32 s10, s62, 0x20000
	s_addc_u32 s11, s63, 0
	s_mov_b32 m0, s94
	v_lshl_add_u64 v[248:249], s[10:11], 0, v[154:155]
	ds_read_b128 v[214:217], v171 offset:32768
	ds_read_b128 v[218:221], v171 offset:33792
	ds_read_b128 v[222:225], v171 offset:34816
	ds_read_b128 v[226:229], v171 offset:35840
	ds_read_b128 v[230:233], v171 offset:36864
	ds_read_b128 v[234:237], v171 offset:37888
	ds_read_b128 v[238:241], v171 offset:38912
	ds_read_b128 v[242:245], v171 offset:39936
	global_load_lds_dwordx4 v[248:249], off
	v_lshl_add_u64 v[248:249], s[10:11], 0, v[152:153]
	s_mov_b32 m0, s95
	s_nop 0
	global_load_lds_dwordx4 v[248:249], off
	s_waitcnt vmcnt(8)
	s_waitcnt lgkmcnt(0)
	s_barrier
	s_waitcnt lgkmcnt(0)
	v_mfma_f32_16x16x32_bf16 v[126:129], v[160:163], v[214:217], v[126:129]
	v_mfma_f32_16x16x32_bf16 v[122:125], v[186:189], v[214:217], v[122:125]
	v_mfma_f32_16x16x32_bf16 v[110:113], v[160:163], v[222:225], v[110:113]
	v_mfma_f32_16x16x32_bf16 v[106:109], v[186:189], v[222:225], v[106:109]
	v_mfma_f32_16x16x32_bf16 v[94:97], v[160:163], v[230:233], v[94:97]
	v_mfma_f32_16x16x32_bf16 v[90:93], v[186:189], v[230:233], v[90:93]
	v_mfma_f32_16x16x32_bf16 v[78:81], v[160:163], v[238:241], v[78:81]
	v_mfma_f32_16x16x32_bf16 v[74:77], v[186:189], v[238:241], v[74:77]
	v_mfma_f32_16x16x32_bf16 v[126:129], v[164:167], v[218:221], v[126:129]
	v_mfma_f32_16x16x32_bf16 v[122:125], v[190:193], v[218:221], v[122:125]
	v_mfma_f32_16x16x32_bf16 v[110:113], v[164:167], v[226:229], v[110:113]
	v_mfma_f32_16x16x32_bf16 v[106:109], v[190:193], v[226:229], v[106:109]
	v_mfma_f32_16x16x32_bf16 v[94:97], v[164:167], v[234:237], v[94:97]
	v_mfma_f32_16x16x32_bf16 v[90:93], v[190:193], v[234:237], v[90:93]
	v_mfma_f32_16x16x32_bf16 v[78:81], v[164:167], v[242:245], v[78:81]
	v_mfma_f32_16x16x32_bf16 v[74:77], v[190:193], v[242:245], v[74:77]
	v_mfma_f32_16x16x32_bf16 v[118:121], v[198:201], v[214:217], v[118:121]
	v_mfma_f32_16x16x32_bf16 v[114:117], v[206:209], v[214:217], v[114:117]
	v_mfma_f32_16x16x32_bf16 v[102:105], v[198:201], v[222:225], v[102:105]
	v_mfma_f32_16x16x32_bf16 v[98:101], v[206:209], v[222:225], v[98:101]
	v_mfma_f32_16x16x32_bf16 v[86:89], v[198:201], v[230:233], v[86:89]
	v_mfma_f32_16x16x32_bf16 v[82:85], v[206:209], v[230:233], v[82:85]
	v_mfma_f32_16x16x32_bf16 v[70:73], v[198:201], v[238:241], v[70:73]
	v_mfma_f32_16x16x32_bf16 v[66:69], v[206:209], v[238:241], v[66:69]
	v_mfma_f32_16x16x32_bf16 v[118:121], v[202:205], v[218:221], v[118:121]
	v_mfma_f32_16x16x32_bf16 v[114:117], v[210:213], v[218:221], v[114:117]
	v_mfma_f32_16x16x32_bf16 v[102:105], v[202:205], v[226:229], v[102:105]
	v_mfma_f32_16x16x32_bf16 v[98:101], v[210:213], v[226:229], v[98:101]
	v_mfma_f32_16x16x32_bf16 v[86:89], v[202:205], v[234:237], v[86:89]
	v_mfma_f32_16x16x32_bf16 v[82:85], v[210:213], v[234:237], v[82:85]
	v_mfma_f32_16x16x32_bf16 v[70:73], v[202:205], v[242:245], v[70:73]
	v_mfma_f32_16x16x32_bf16 v[66:69], v[210:213], v[242:245], v[66:69]
	s_barrier
; #define PG8_STAGE(bufoff, gbase, voff) do { _Pragma("unroll") for (int _i = 0; _i < 2; ++_i) \
;         __builtin_amdgcn_global_load_lds((const unsigned*)((const char*)(gbase) + (voff)[_i]), (PG8_LAS unsigned*)(lds + (bufoff) + ldsw + _i * 8192), 16, 0, 0); } while (0)
; #define PG8_LDA(dst, b, h) do { _Pragma("unroll") for (int m = 0; m < 4; ++m) _Pragma("unroll") for (int k = 0; k < 2; ++k) dst[m][k] = *(const PG8_LAS bf16x8*)(lds + PG8_SA(b, h) + aoff + m * 2048 + k * 1024); } while (0)
; #define PG8_MMA(ai, bj, At, Bt) do { __builtin_amdgcn_s_setprio(1); _Pragma("unroll") for (int m = 0; m < 4; ++m) _Pragma("unroll") for (int n = 0; n < 2; ++n) _Pragma("unroll") for (int k = 0; k < 2; ++k) \
;         acc[ai][bj][m][n] = __builtin_amdgcn_mfma_f32_16x16x32_bf16(Bt[n][k], At[m][k], acc[ai][bj][m][n], 0, 0, 0); __builtin_amdgcn_s_setprio(0); } while (0)
; #define PG8_WAIT_V(n) asm volatile("s_waitcnt vmcnt(" #n ")" ::: "memory")
; #define PG8_WAIT_L(n) asm volatile("s_waitcnt lgkmcnt(" #n ")" ::: "memory")
; #define PG8_BAR __builtin_amdgcn_s_barrier()
; #define PG8_SCHED __builtin_amdgcn_sched_barrier(0)
; template <class Epi, class Sched, bool ALIGN_EPI = false, bool SP2 = false>
; __device__ __forceinline__ void gemm_phase(PG8_LAS unsigned char* lds, const Gemm g, const Sched& S, const Epi& E) {
;     ...
;         for (int t = 0; t < nt; t += 2) {
;             const bool last = (t == nt - 2);
;             const char* a1 = cA + (size_t)(t + 1) * kstep;
;             const char* a2 = last ? nA : cA + (size_t)(t + 2) * kstep; const char* b2 = last ? nB : cB + (size_t)(t + 2) * kstep;
;             const char* a3 = a2 + kstep; const char* b3 = b2 + kstep;
;             if (last && has_next) S.a_ready(nxt);
;     ...
;             PG8_LDA(At, 1, 1); PG8_STAGE(PG8_SB(1, 0), b3, voffB); PG8_STAGE(PG8_SB(1, 1), b3 + hstepB, voffB); PG8_STAGE(PG8_SA(1, 0), a3, voffA);
;             PG8_WAIT_V(8); PG8_WAIT_L(0); PG8_BAR; PG8_MMA(1, 0, At, B0); PG8_MMA(1, 1, At, B1); PG8_BAR; PG8_SCHED;
	s_add_i32 s10, s12, s68
	v_lshl_add_u64 v[130:131], v[130:131], 0, s[2:3]
	s_mov_b32 m0, s10
	ds_read_b128 v[214:217], v171 offset:49152
	ds_read_b128 v[218:221], v171 offset:50176
	ds_read_b128 v[222:225], v171 offset:51200
	ds_read_b128 v[226:229], v171 offset:52224
	ds_read_b128 v[230:233], v171 offset:53248
	ds_read_b128 v[234:237], v171 offset:54272
	ds_read_b128 v[238:241], v171 offset:55296
	ds_read_b128 v[242:245], v171 offset:56320
	global_load_lds_dwordx4 v[130:131], off
	s_add_i32 m0, s10, 0x2000
	s_add_u32 s10, s56, 0x20080
	v_lshl_add_u64 v[130:131], v[132:133], 0, s[2:3]
	s_addc_u32 s11, s57, 0
	s_add_i32 s12, s13, s68
	global_load_lds_dwordx4 v[130:131], off
	v_lshl_add_u64 v[130:131], s[10:11], 0, v[0:1]
	s_mov_b32 m0, s12
	s_nop 0
	global_load_lds_dwordx4 v[130:131], off
	v_lshl_add_u64 v[130:131], s[10:11], 0, v[150:151]
	s_add_i32 m0, s12, 0x2000
	s_nop 0
	global_load_lds_dwordx4 v[130:131], off
	v_lshl_add_u64 v[130:131], v[172:173], 0, s[2:3]
	s_mov_b32 m0, s8
	s_nop 0
	global_load_lds_dwordx4 v[130:131], off
	v_lshl_add_u64 v[130:131], v[246:247], 0, s[2:3]
	s_mov_b32 m0, s9
	s_nop 0
	global_load_lds_dwordx4 v[130:131], off
	s_waitcnt vmcnt(8)
	s_waitcnt lgkmcnt(0)
	s_barrier
	s_waitcnt lgkmcnt(0)
	v_mfma_f32_16x16x32_bf16 v[62:65], v[160:163], v[214:217], v[62:65]
	v_mfma_f32_16x16x32_bf16 v[58:61], v[186:189], v[214:217], v[58:61]
	s_add_i32 vcc_hi, vcc_hi, 2
	v_mfma_f32_16x16x32_bf16 v[46:49], v[160:163], v[222:225], v[46:49]
	s_add_u32 s54, s54, 0x100
	v_mfma_f32_16x16x32_bf16 v[42:45], v[186:189], v[222:225], v[42:45]
	s_addc_u32 s55, s55, 0
	v_mfma_f32_16x16x32_bf16 v[30:33], v[160:163], v[230:233], v[30:33]
	s_add_u32 s91, s91, 0x100
	v_mfma_f32_16x16x32_bf16 v[26:29], v[186:189], v[230:233], v[26:29]
	s_addc_u32 vcc_lo, vcc_lo, 0
	v_mfma_f32_16x16x32_bf16 v[14:17], v[160:163], v[238:241], v[14:17]
	s_add_u32 s10, s54, 0xfffe0080
	v_mfma_f32_16x16x32_bf16 v[10:13], v[186:189], v[238:241], v[10:13]
	s_addc_u32 s11, s55, -1
	v_mfma_f32_16x16x32_bf16 v[62:65], v[164:167], v[218:221], v[62:65]
	s_add_i32 s12, 0, 0x10000
	v_mfma_f32_16x16x32_bf16 v[58:61], v[190:193], v[218:221], v[58:61]
	s_cmp_eq_u32 vcc_hi, 4
	v_mfma_f32_16x16x32_bf16 v[46:49], v[164:167], v[226:229], v[46:49]
	s_cselect_b32 s63, s41, s11
	v_mfma_f32_16x16x32_bf16 v[42:45], v[190:193], v[226:229], v[42:45]
	s_cselect_b32 s62, s47, s10
	v_mfma_f32_16x16x32_bf16 v[30:33], v[164:167], v[234:237], v[30:33]
	v_add_u32_e32 v130, s12, v169
	v_mfma_f32_16x16x32_bf16 v[26:29], v[190:193], v[234:237], v[26:29]
	s_cselect_b32 s57, s4, vcc_lo
	v_mfma_f32_16x16x32_bf16 v[14:17], v[164:167], v[242:245], v[14:17]
	s_cselect_b32 s56, s45, s91
	v_mfma_f32_16x16x32_bf16 v[10:13], v[190:193], v[242:245], v[10:13]
	s_add_i32 s13, 0, 0x14000
	v_mfma_f32_16x16x32_bf16 v[54:57], v[198:201], v[214:217], v[54:57]
	s_cmp_gt_u32 vcc_hi, 5
	v_mfma_f32_16x16x32_bf16 v[50:53], v[206:209], v[214:217], v[50:53]
	v_mfma_f32_16x16x32_bf16 v[38:41], v[198:201], v[222:225], v[38:41]
	v_mfma_f32_16x16x32_bf16 v[34:37], v[206:209], v[222:225], v[34:37]
	v_mfma_f32_16x16x32_bf16 v[22:25], v[198:201], v[230:233], v[22:25]
	v_mfma_f32_16x16x32_bf16 v[18:21], v[206:209], v[230:233], v[18:21]
	v_mfma_f32_16x16x32_bf16 v[6:9], v[198:201], v[238:241], v[6:9]
	v_mfma_f32_16x16x32_bf16 v[2:5], v[206:209], v[238:241], v[2:5]
	v_mfma_f32_16x16x32_bf16 v[54:57], v[202:205], v[218:221], v[54:57]
	v_mfma_f32_16x16x32_bf16 v[50:53], v[210:213], v[218:221], v[50:53]
	v_mfma_f32_16x16x32_bf16 v[38:41], v[202:205], v[226:229], v[38:41]
	v_mfma_f32_16x16x32_bf16 v[34:37], v[210:213], v[226:229], v[34:37]
	v_mfma_f32_16x16x32_bf16 v[22:25], v[202:205], v[234:237], v[22:25]
	v_mfma_f32_16x16x32_bf16 v[18:21], v[210:213], v[234:237], v[18:21]
	v_mfma_f32_16x16x32_bf16 v[6:9], v[202:205], v[242:245], v[6:9]
	v_mfma_f32_16x16x32_bf16 v[2:5], v[210:213], v[242:245], v[2:5]
	s_barrier
	s_cbranch_scc0 .Lgk_623
	s_and_b64 vcc, exec, s[42:43]
	s_cbranch_vccz .LBB0_626
	s_barrier

; #define PG8_STAGE(bufoff, gbase, voff) do { _Pragma("unroll") for (int _i = 0; _i < 2; ++_i) \
;         __builtin_amdgcn_global_load_lds((const unsigned*)((const char*)(gbase) + (voff)[_i]), (PG8_LAS unsigned*)(lds + (bufoff) + ldsw + _i * 8192), 16, 0, 0); } while (0)
; #define PG8_LDA(dst, b, h) do { _Pragma("unroll") for (int m = 0; m < 4; ++m) _Pragma("unroll") for (int k = 0; k < 2; ++k) dst[m][k] = *(const PG8_LAS bf16x8*)(lds + PG8_SA(b, h) + aoff + m * 2048 + k * 1024); } while (0)
; #define PG8_LDB(dst, b, h) do { _Pragma("unroll") for (int n = 0; n < 2; ++n) _Pragma("unroll") for (int k = 0; k < 2; ++k) dst[n][k] = *(const PG8_LAS bf16x8*)(lds + PG8_SB(b, h) + boff + n * 2048 + k * 1024); } while (0)
; #define PG8_MMA(ai, bj, At, Bt) do { __builtin_amdgcn_s_setprio(1); _Pragma("unroll") for (int m = 0; m < 4; ++m) _Pragma("unroll") for (int n = 0; n < 2; ++n) _Pragma("unroll") for (int k = 0; k < 2; ++k) \
;         acc[ai][bj][m][n] = __builtin_amdgcn_mfma_f32_16x16x32_bf16(Bt[n][k], At[m][k], acc[ai][bj][m][n], 0, 0, 0); __builtin_amdgcn_s_setprio(0); } while (0)
; #define PG8_WAIT_V(n) asm volatile("s_waitcnt vmcnt(" #n ")" ::: "memory")
; #define PG8_WAIT_L(n) asm volatile("s_waitcnt lgkmcnt(" #n ")" ::: "memory")
; #define PG8_BAR __builtin_amdgcn_s_barrier()
; #define PG8_SCHED __builtin_amdgcn_sched_barrier(0)
; template <class Epi, class Sched, bool ALIGN_EPI = false, bool SP2 = false>
; __device__ __forceinline__ void gemm_phase(PG8_LAS unsigned char* lds, const Gemm g, const Sched& S, const Epi& E) {
;     ...
;             PG8_LDB(B0, 0, 0); PG8_LDB(B1, 0, 1); PG8_SCHED; PG8_LDA(At, 0, 0); PG8_STAGE(PG8_SA(1, 1), a1 + hstepA, voffA);
;             PG8_WAIT_V(8); PG8_WAIT_L(0); PG8_BAR; PG8_MMA(0, 0, At, B0); PG8_MMA(0, 1, At, B1); PG8_BAR; PG8_SCHED;
;             PG8_LDA(At, 0, 1); PG8_STAGE(PG8_SB(0, 0), b2, voffB); PG8_STAGE(PG8_SB(0, 1), b2 + hstepB, voffB); PG8_STAGE(PG8_SA(0, 0), a2, voffA);
;             PG8_WAIT_V(8); PG8_WAIT_L(0); PG8_BAR; PG8_MMA(1, 0, At, B0); PG8_MMA(1, 1, At, B1); PG8_BAR; PG8_SCHED;
;             PG8_LDB(B0, 1, 0); PG8_LDB(B1, 1, 1); PG8_SCHED; PG8_LDA(At, 1, 0); PG8_STAGE(PG8_SA(0, 1), a2 + hstepA, voffA);
;             PG8_WAIT_V(8); PG8_WAIT_L(0); PG8_BAR; PG8_MMA(0, 0, At, B0); PG8_MMA(0, 1, At, B1); PG8_BAR; PG8_SCHED;
.Lgk_929:
	ds_read_b128 v[160:163], v130
	ds_read_b128 v[170:173], v130 offset:1024
	ds_read_b128 v[186:189], v130 offset:2048
	ds_read_b128 v[190:193], v130 offset:3072
	v_add_u32_e32 v130, s13, v167
	ds_read_b128 v[198:201], v130
	ds_read_b128 v[202:205], v130 offset:1024
	ds_read_b128 v[206:209], v130 offset:2048
	ds_read_b128 v[210:213], v130 offset:3072
	v_lshl_add_u64 v[130:131], s[46:47], 0, v[156:157]
	s_add_i32 m0, s9, 0xc000
	ds_read_b128 v[214:217], v169
	ds_read_b128 v[218:221], v169 offset:1024
	ds_read_b128 v[222:225], v169 offset:2048
	ds_read_b128 v[226:229], v169 offset:3072
	ds_read_b128 v[230:233], v169 offset:4096
	ds_read_b128 v[234:237], v169 offset:5120
	ds_read_b128 v[238:241], v169 offset:6144
	ds_read_b128 v[242:245], v169 offset:7168
	global_load_lds_dwordx4 v[130:131], off
	v_lshl_add_u64 v[130:131], s[46:47], 0, v[158:159]
	s_add_i32 m0, s9, 0xe000
	s_nop 0
	global_load_lds_dwordx4 v[130:131], off
	s_waitcnt vmcnt(8)
	s_waitcnt lgkmcnt(0)
	s_barrier
	s_waitcnt lgkmcnt(0)
	v_mfma_f32_16x16x32_bf16 v[126:129], v[160:163], v[214:217], v[126:129]
	v_mfma_f32_16x16x32_bf16 v[122:125], v[186:189], v[214:217], v[122:125]
	v_mfma_f32_16x16x32_bf16 v[110:113], v[160:163], v[222:225], v[110:113]
	v_mfma_f32_16x16x32_bf16 v[106:109], v[186:189], v[222:225], v[106:109]
	v_mfma_f32_16x16x32_bf16 v[94:97], v[160:163], v[230:233], v[94:97]
	v_mfma_f32_16x16x32_bf16 v[90:93], v[186:189], v[230:233], v[90:93]
	v_mfma_f32_16x16x32_bf16 v[78:81], v[160:163], v[238:241], v[78:81]
	v_mfma_f32_16x16x32_bf16 v[74:77], v[186:189], v[238:241], v[74:77]
	v_mfma_f32_16x16x32_bf16 v[126:129], v[170:173], v[218:221], v[126:129]
	v_mfma_f32_16x16x32_bf16 v[122:125], v[190:193], v[218:221], v[122:125]
	v_mfma_f32_16x16x32_bf16 v[110:113], v[170:173], v[226:229], v[110:113]
	v_mfma_f32_16x16x32_bf16 v[106:109], v[190:193], v[226:229], v[106:109]
	v_mfma_f32_16x16x32_bf16 v[94:97], v[170:173], v[234:237], v[94:97]
	v_mfma_f32_16x16x32_bf16 v[90:93], v[190:193], v[234:237], v[90:93]
	v_mfma_f32_16x16x32_bf16 v[78:81], v[170:173], v[242:245], v[78:81]
	v_mfma_f32_16x16x32_bf16 v[74:77], v[190:193], v[242:245], v[74:77]
	v_mfma_f32_16x16x32_bf16 v[118:121], v[198:201], v[214:217], v[118:121]
	v_mfma_f32_16x16x32_bf16 v[114:117], v[206:209], v[214:217], v[114:117]
	v_mfma_f32_16x16x32_bf16 v[102:105], v[198:201], v[222:225], v[102:105]
	v_mfma_f32_16x16x32_bf16 v[98:101], v[206:209], v[222:225], v[98:101]
	v_mfma_f32_16x16x32_bf16 v[86:89], v[198:201], v[230:233], v[86:89]
	v_mfma_f32_16x16x32_bf16 v[82:85], v[206:209], v[230:233], v[82:85]
	v_mfma_f32_16x16x32_bf16 v[70:73], v[198:201], v[238:241], v[70:73]
	v_mfma_f32_16x16x32_bf16 v[66:69], v[206:209], v[238:241], v[66:69]
	v_mfma_f32_16x16x32_bf16 v[118:121], v[202:205], v[218:221], v[118:121]
	v_mfma_f32_16x16x32_bf16 v[114:117], v[210:213], v[218:221], v[114:117]
	v_mfma_f32_16x16x32_bf16 v[102:105], v[202:205], v[226:229], v[102:105]
	v_mfma_f32_16x16x32_bf16 v[98:101], v[210:213], v[226:229], v[98:101]
	v_mfma_f32_16x16x32_bf16 v[86:89], v[202:205], v[234:237], v[86:89]
	v_mfma_f32_16x16x32_bf16 v[82:85], v[210:213], v[234:237], v[82:85]
	v_mfma_f32_16x16x32_bf16 v[70:73], v[202:205], v[242:245], v[70:73]
	v_mfma_f32_16x16x32_bf16 v[66:69], v[210:213], v[242:245], v[66:69]
	s_barrier
	s_add_i32 s10, s12, s8
	v_lshl_add_u64 v[130:131], s[48:49], 0, v[0:1]
	s_mov_b32 m0, s10
	ds_read_b128 v[214:217], v169 offset:16384
	ds_read_b128 v[218:221], v169 offset:17408
	ds_read_b128 v[222:225], v169 offset:18432
	ds_read_b128 v[226:229], v169 offset:19456
	ds_read_b128 v[230:233], v169 offset:20480
	ds_read_b128 v[234:237], v169 offset:21504
	ds_read_b128 v[238:241], v169 offset:22528
	ds_read_b128 v[242:245], v169 offset:23552
	global_load_lds_dwordx4 v[130:131], off
	s_add_i32 m0, s10, 0x2000
	s_add_u32 s10, s48, 0x100000
	v_lshl_add_u64 v[132:133], s[48:49], 0, v[150:151]
	s_addc_u32 s11, s49, 0
	s_add_i32 s12, s13, s8
	global_load_lds_dwordx4 v[132:133], off
	v_lshl_add_u64 v[164:165], s[10:11], 0, v[0:1]
	s_mov_b32 m0, s12
	v_lshl_add_u64 v[246:247], s[50:51], 0, v[152:153]
	global_load_lds_dwordx4 v[164:165], off
	v_lshl_add_u64 v[164:165], s[10:11], 0, v[150:151]
	s_add_i32 m0, s12, 0x2000
	s_nop 0
	global_load_lds_dwordx4 v[164:165], off
	v_lshl_add_u64 v[164:165], s[50:51], 0, v[154:155]
	s_mov_b32 m0, s9
	s_nop 0
	global_load_lds_dwordx4 v[164:165], off
	s_mov_b32 m0, s30
	s_nop 0
	global_load_lds_dwordx4 v[246:247], off
	s_waitcnt vmcnt(8)
	s_waitcnt lgkmcnt(0)
	s_barrier
	s_waitcnt lgkmcnt(0)
	v_mfma_f32_16x16x32_bf16 v[62:65], v[160:163], v[214:217], v[62:65]
	v_mfma_f32_16x16x32_bf16 v[58:61], v[186:189], v[214:217], v[58:61]
	v_mfma_f32_16x16x32_bf16 v[46:49], v[160:163], v[222:225], v[46:49]
	v_mfma_f32_16x16x32_bf16 v[42:45], v[186:189], v[222:225], v[42:45]
	v_mfma_f32_16x16x32_bf16 v[30:33], v[160:163], v[230:233], v[30:33]
	v_mfma_f32_16x16x32_bf16 v[26:29], v[186:189], v[230:233], v[26:29]
	v_mfma_f32_16x16x32_bf16 v[14:17], v[160:163], v[238:241], v[14:17]
	v_mfma_f32_16x16x32_bf16 v[10:13], v[186:189], v[238:241], v[10:13]
	v_mfma_f32_16x16x32_bf16 v[62:65], v[170:173], v[218:221], v[62:65]
	v_mfma_f32_16x16x32_bf16 v[58:61], v[190:193], v[218:221], v[58:61]
	v_mfma_f32_16x16x32_bf16 v[46:49], v[170:173], v[226:229], v[46:49]
	v_mfma_f32_16x16x32_bf16 v[42:45], v[190:193], v[226:229], v[42:45]
	v_mfma_f32_16x16x32_bf16 v[30:33], v[170:173], v[234:237], v[30:33]
	v_mfma_f32_16x16x32_bf16 v[26:29], v[190:193], v[234:237], v[26:29]
	v_mfma_f32_16x16x32_bf16 v[14:17], v[170:173], v[242:245], v[14:17]
	v_mfma_f32_16x16x32_bf16 v[10:13], v[190:193], v[242:245], v[10:13]
	v_mfma_f32_16x16x32_bf16 v[54:57], v[198:201], v[214:217], v[54:57]
	v_mfma_f32_16x16x32_bf16 v[50:53], v[206:209], v[214:217], v[50:53]
	v_mfma_f32_16x16x32_bf16 v[38:41], v[198:201], v[222:225], v[38:41]
	v_mfma_f32_16x16x32_bf16 v[34:37], v[206:209], v[222:225], v[34:37]
	v_mfma_f32_16x16x32_bf16 v[22:25], v[198:201], v[230:233], v[22:25]
	v_mfma_f32_16x16x32_bf16 v[18:21], v[206:209], v[230:233], v[18:21]
	v_mfma_f32_16x16x32_bf16 v[6:9], v[198:201], v[238:241], v[6:9]
	v_mfma_f32_16x16x32_bf16 v[2:5], v[206:209], v[238:241], v[2:5]
	v_mfma_f32_16x16x32_bf16 v[54:57], v[202:205], v[218:221], v[54:57]
	v_mfma_f32_16x16x32_bf16 v[50:53], v[210:213], v[218:221], v[50:53]
	v_mfma_f32_16x16x32_bf16 v[38:41], v[202:205], v[226:229], v[38:41]
	v_mfma_f32_16x16x32_bf16 v[34:37], v[210:213], v[226:229], v[34:37]
	v_mfma_f32_16x16x32_bf16 v[22:25], v[202:205], v[234:237], v[22:25]
	v_mfma_f32_16x16x32_bf16 v[18:21], v[210:213], v[234:237], v[18:21]
	v_mfma_f32_16x16x32_bf16 v[6:9], v[202:205], v[242:245], v[6:9]
	v_mfma_f32_16x16x32_bf16 v[2:5], v[210:213], v[242:245], v[2:5]
	s_barrier
; #define PG8_STAGE(bufoff, gbase, voff) do { _Pragma("unroll") for (int _i = 0; _i < 2; ++_i) \
;         __builtin_amdgcn_global_load_lds((const unsigned*)((const char*)(gbase) + (voff)[_i]), (PG8_LAS unsigned*)(lds + (bufoff) + ldsw + _i * 8192), 16, 0, 0); } while (0)
; #define PG8_LDA(dst, b, h) do { _Pragma("unroll") for (int m = 0; m < 4; ++m) _Pragma("unroll") for (int k = 0; k < 2; ++k) dst[m][k] = *(const PG8_LAS bf16x8*)(lds + PG8_SA(b, h) + aoff + m * 2048 + k * 1024); } while (0)
; #define PG8_LDB(dst, b, h) do { _Pragma("unroll") for (int n = 0; n < 2; ++n) _Pragma("unroll") for (int k = 0; k < 2; ++k) dst[n][k] = *(const PG8_LAS bf16x8*)(lds + PG8_SB(b, h) + boff + n * 2048 + k * 1024); } while (0)
; #define PG8_MMA(ai, bj, At, Bt) do { __builtin_amdgcn_s_setprio(1); _Pragma("unroll") for (int m = 0; m < 4; ++m) _Pragma("unroll") for (int n = 0; n < 2; ++n) _Pragma("unroll") for (int k = 0; k < 2; ++k) \
;         acc[ai][bj][m][n] = __builtin_amdgcn_mfma_f32_16x16x32_bf16(Bt[n][k], At[m][k], acc[ai][bj][m][n], 0, 0, 0); __builtin_amdgcn_s_setprio(0); } while (0)
; #define PG8_WAIT_V(n) asm volatile("s_waitcnt vmcnt(" #n ")" ::: "memory")
; #define PG8_WAIT_L(n) asm volatile("s_waitcnt lgkmcnt(" #n ")" ::: "memory")
; #define PG8_BAR __builtin_amdgcn_s_barrier()
; #define PG8_SCHED __builtin_amdgcn_sched_barrier(0)
; template <class Epi, class Sched, bool ALIGN_EPI = false, bool SP2 = false>
; __device__ __forceinline__ void gemm_phase(PG8_LAS unsigned char* lds, const Gemm g, const Sched& S, const Epi& E) {
;     ...
;             PG8_LDB(B0, 1, 0); PG8_LDB(B1, 1, 1); PG8_SCHED; PG8_LDA(At, 1, 0); PG8_STAGE(PG8_SA(0, 1), a2 + hstepA, voffA);
;             PG8_WAIT_V(8); PG8_WAIT_L(0); PG8_BAR; PG8_MMA(0, 0, At, B0); PG8_MMA(0, 1, At, B1); PG8_BAR; PG8_SCHED;
	s_add_i32 s12, 0, 0x18000
	s_add_i32 s13, 0, 0x1c000
	v_add_u32_e32 v190, s12, v167
	v_add_u32_e32 v210, s13, v167
	ds_read_b128 v[160:163], v190
	ds_read_b128 v[170:173], v190 offset:1024
	ds_read_b128 v[186:189], v190 offset:2048
	ds_read_b128 v[190:193], v190 offset:3072
	ds_read_b128 v[198:201], v210
	ds_read_b128 v[202:205], v210 offset:1024
	ds_read_b128 v[206:209], v210 offset:2048
	ds_read_b128 v[210:213], v210 offset:3072
	s_add_u32 s10, s50, 0x100000
	s_addc_u32 s11, s51, 0
	s_mov_b32 m0, s31
	v_lshl_add_u64 v[248:249], s[10:11], 0, v[154:155]
	ds_read_b128 v[214:217], v169 offset:32768
	ds_read_b128 v[218:221], v169 offset:33792
	ds_read_b128 v[222:225], v169 offset:34816
	ds_read_b128 v[226:229], v169 offset:35840
	ds_read_b128 v[230:233], v169 offset:36864
	ds_read_b128 v[234:237], v169 offset:37888
	ds_read_b128 v[238:241], v169 offset:38912
	ds_read_b128 v[242:245], v169 offset:39936
	global_load_lds_dwordx4 v[248:249], off
	v_lshl_add_u64 v[248:249], s[10:11], 0, v[152:153]
	s_mov_b32 m0, s34
	s_nop 0
	global_load_lds_dwordx4 v[248:249], off
	s_waitcnt vmcnt(8)
	s_waitcnt lgkmcnt(0)
	s_barrier
	s_waitcnt lgkmcnt(0)
	v_mfma_f32_16x16x32_bf16 v[126:129], v[160:163], v[214:217], v[126:129]
	v_mfma_f32_16x16x32_bf16 v[122:125], v[186:189], v[214:217], v[122:125]
	v_mfma_f32_16x16x32_bf16 v[110:113], v[160:163], v[222:225], v[110:113]
	v_mfma_f32_16x16x32_bf16 v[106:109], v[186:189], v[222:225], v[106:109]
	v_mfma_f32_16x16x32_bf16 v[94:97], v[160:163], v[230:233], v[94:97]
	v_mfma_f32_16x16x32_bf16 v[90:93], v[186:189], v[230:233], v[90:93]
	v_mfma_f32_16x16x32_bf16 v[78:81], v[160:163], v[238:241], v[78:81]
	v_mfma_f32_16x16x32_bf16 v[74:77], v[186:189], v[238:241], v[74:77]
	v_mfma_f32_16x16x32_bf16 v[126:129], v[170:173], v[218:221], v[126:129]
	v_mfma_f32_16x16x32_bf16 v[122:125], v[190:193], v[218:221], v[122:125]
	v_mfma_f32_16x16x32_bf16 v[110:113], v[170:173], v[226:229], v[110:113]
	v_mfma_f32_16x16x32_bf16 v[106:109], v[190:193], v[226:229], v[106:109]
	v_mfma_f32_16x16x32_bf16 v[94:97], v[170:173], v[234:237], v[94:97]
	v_mfma_f32_16x16x32_bf16 v[90:93], v[190:193], v[234:237], v[90:93]
	v_mfma_f32_16x16x32_bf16 v[78:81], v[170:173], v[242:245], v[78:81]
	v_mfma_f32_16x16x32_bf16 v[74:77], v[190:193], v[242:245], v[74:77]
	v_mfma_f32_16x16x32_bf16 v[118:121], v[198:201], v[214:217], v[118:121]
	v_mfma_f32_16x16x32_bf16 v[114:117], v[206:209], v[214:217], v[114:117]
	v_mfma_f32_16x16x32_bf16 v[102:105], v[198:201], v[222:225], v[102:105]
	v_mfma_f32_16x16x32_bf16 v[98:101], v[206:209], v[222:225], v[98:101]
	v_mfma_f32_16x16x32_bf16 v[86:89], v[198:201], v[230:233], v[86:89]
	v_mfma_f32_16x16x32_bf16 v[82:85], v[206:209], v[230:233], v[82:85]
	v_mfma_f32_16x16x32_bf16 v[70:73], v[198:201], v[238:241], v[70:73]
	v_mfma_f32_16x16x32_bf16 v[66:69], v[206:209], v[238:241], v[66:69]
	v_mfma_f32_16x16x32_bf16 v[118:121], v[202:205], v[218:221], v[118:121]
	v_mfma_f32_16x16x32_bf16 v[114:117], v[210:213], v[218:221], v[114:117]
	v_mfma_f32_16x16x32_bf16 v[102:105], v[202:205], v[226:229], v[102:105]
	v_mfma_f32_16x16x32_bf16 v[98:101], v[210:213], v[226:229], v[98:101]
	v_mfma_f32_16x16x32_bf16 v[86:89], v[202:205], v[234:237], v[86:89]
	v_mfma_f32_16x16x32_bf16 v[82:85], v[210:213], v[234:237], v[82:85]
	v_mfma_f32_16x16x32_bf16 v[70:73], v[202:205], v[242:245], v[70:73]
	v_mfma_f32_16x16x32_bf16 v[66:69], v[210:213], v[242:245], v[66:69]
	s_barrier
; #define PG8_STAGE(bufoff, gbase, voff) do { _Pragma("unroll") for (int _i = 0; _i < 2; ++_i) \
;         __builtin_amdgcn_global_load_lds((const unsigned*)((const char*)(gbase) + (voff)[_i]), (PG8_LAS unsigned*)(lds + (bufoff) + ldsw + _i * 8192), 16, 0, 0); } while (0)
; #define PG8_LDA(dst, b, h) do { _Pragma("unroll") for (int m = 0; m < 4; ++m) _Pragma("unroll") for (int k = 0; k < 2; ++k) dst[m][k] = *(const PG8_LAS bf16x8*)(lds + PG8_SA(b, h) + aoff + m * 2048 + k * 1024); } while (0)
; #define PG8_MMA(ai, bj, At, Bt) do { __builtin_amdgcn_s_setprio(1); _Pragma("unroll") for (int m = 0; m < 4; ++m) _Pragma("unroll") for (int n = 0; n < 2; ++n) _Pragma("unroll") for (int k = 0; k < 2; ++k) \
;         acc[ai][bj][m][n] = __builtin_amdgcn_mfma_f32_16x16x32_bf16(Bt[n][k], At[m][k], acc[ai][bj][m][n], 0, 0, 0); __builtin_amdgcn_s_setprio(0); } while (0)
; #define PG8_WAIT_V(n) asm volatile("s_waitcnt vmcnt(" #n ")" ::: "memory")
; #define PG8_WAIT_L(n) asm volatile("s_waitcnt lgkmcnt(" #n ")" ::: "memory")
; #define PG8_BAR __builtin_amdgcn_s_barrier()
; #define PG8_SCHED __builtin_amdgcn_sched_barrier(0)
; template <class Epi, class Sched, bool ALIGN_EPI = false, bool SP2 = false>
; __device__ __forceinline__ void gemm_phase(PG8_LAS unsigned char* lds, const Gemm g, const Sched& S, const Epi& E) {
;     ...
;         for (int t = 0; t < nt; t += 2) {
;             const bool last = (t == nt - 2);
;             const char* a1 = cA + (size_t)(t + 1) * kstep;
;             const char* a2 = last ? nA : cA + (size_t)(t + 2) * kstep; const char* b2 = last ? nB : cB + (size_t)(t + 2) * kstep;
;             const char* a3 = a2 + kstep; const char* b3 = b2 + kstep;
;             if (last && has_next) S.a_ready(nxt);
;     ...
;             PG8_LDA(At, 1, 1); PG8_STAGE(PG8_SB(1, 0), b3, voffB); PG8_STAGE(PG8_SB(1, 1), b3 + hstepB, voffB); PG8_STAGE(PG8_SA(1, 0), a3, voffA);
;             PG8_WAIT_V(8); PG8_WAIT_L(0); PG8_BAR; PG8_MMA(1, 0, At, B0); PG8_MMA(1, 1, At, B1); PG8_BAR; PG8_SCHED;
	s_add_i32 s10, s12, s8
	v_lshl_add_u64 v[130:131], v[130:131], 0, s[2:3]
	s_mov_b32 m0, s10
	ds_read_b128 v[214:217], v169 offset:49152
	ds_read_b128 v[218:221], v169 offset:50176
	ds_read_b128 v[222:225], v169 offset:51200
	ds_read_b128 v[226:229], v169 offset:52224
	ds_read_b128 v[230:233], v169 offset:53248
	ds_read_b128 v[234:237], v169 offset:54272
	ds_read_b128 v[238:241], v169 offset:55296
	ds_read_b128 v[242:245], v169 offset:56320
	global_load_lds_dwordx4 v[130:131], off
	s_add_i32 m0, s10, 0x2000
	s_add_u32 s10, s48, 0x100080
	v_lshl_add_u64 v[130:131], v[132:133], 0, s[2:3]
	s_addc_u32 s11, s49, 0
	s_add_i32 s12, s13, s8
	global_load_lds_dwordx4 v[130:131], off
	v_lshl_add_u64 v[130:131], s[10:11], 0, v[0:1]
	s_mov_b32 m0, s12
	s_nop 0
	global_load_lds_dwordx4 v[130:131], off
	v_lshl_add_u64 v[130:131], s[10:11], 0, v[150:151]
	s_add_i32 m0, s12, 0x2000
	s_nop 0
	global_load_lds_dwordx4 v[130:131], off
	v_lshl_add_u64 v[130:131], v[164:165], 0, s[2:3]
	s_mov_b32 m0, s35
	s_nop 0
	global_load_lds_dwordx4 v[130:131], off
	v_lshl_add_u64 v[130:131], v[246:247], 0, s[2:3]
	s_mov_b32 m0, s52
	s_nop 0
	global_load_lds_dwordx4 v[130:131], off
	s_waitcnt vmcnt(8)
	s_waitcnt lgkmcnt(0)
	s_barrier
	s_waitcnt lgkmcnt(0)
	v_mfma_f32_16x16x32_bf16 v[62:65], v[160:163], v[214:217], v[62:65]
	v_mfma_f32_16x16x32_bf16 v[58:61], v[186:189], v[214:217], v[58:61]
	s_add_i32 s63, s63, 2
	v_mfma_f32_16x16x32_bf16 v[46:49], v[160:163], v[222:225], v[46:49]
	s_add_u32 s46, s46, 0x100
	v_mfma_f32_16x16x32_bf16 v[42:45], v[186:189], v[222:225], v[42:45]
	s_addc_u32 s47, s47, 0
	v_mfma_f32_16x16x32_bf16 v[30:33], v[160:163], v[230:233], v[30:33]
	s_add_u32 s57, s57, 0x100
	v_mfma_f32_16x16x32_bf16 v[26:29], v[186:189], v[230:233], v[26:29]
	s_addc_u32 s62, s62, 0
	v_mfma_f32_16x16x32_bf16 v[14:17], v[160:163], v[238:241], v[14:17]
	s_add_u32 s10, s46, 0xfff00080
	v_mfma_f32_16x16x32_bf16 v[10:13], v[186:189], v[238:241], v[10:13]
	s_addc_u32 s11, s47, -1
	v_mfma_f32_16x16x32_bf16 v[62:65], v[170:173], v[218:221], v[62:65]
	s_add_i32 s12, 0, 0x10000
	v_mfma_f32_16x16x32_bf16 v[58:61], v[190:193], v[218:221], v[58:61]
	s_cmp_eq_u32 s63, 60
	v_mfma_f32_16x16x32_bf16 v[46:49], v[170:173], v[226:229], v[46:49]
	s_cselect_b32 s51, s41, s11
	v_mfma_f32_16x16x32_bf16 v[42:45], v[190:193], v[226:229], v[42:45]
	s_cselect_b32 s50, s56, s10
	v_mfma_f32_16x16x32_bf16 v[30:33], v[170:173], v[234:237], v[30:33]
	v_add_u32_e32 v130, s12, v167
	v_mfma_f32_16x16x32_bf16 v[26:29], v[190:193], v[234:237], v[26:29]
	s_cselect_b32 s49, s4, s62
	v_mfma_f32_16x16x32_bf16 v[14:17], v[170:173], v[242:245], v[14:17]
	s_cselect_b32 s48, s39, s57
	v_mfma_f32_16x16x32_bf16 v[10:13], v[190:193], v[242:245], v[10:13]
	s_add_i32 s13, 0, 0x14000
	v_mfma_f32_16x16x32_bf16 v[54:57], v[198:201], v[214:217], v[54:57]
	s_cmp_gt_u32 s63, 61
	v_mfma_f32_16x16x32_bf16 v[50:53], v[206:209], v[214:217], v[50:53]
	v_mfma_f32_16x16x32_bf16 v[38:41], v[198:201], v[222:225], v[38:41]
	v_mfma_f32_16x16x32_bf16 v[34:37], v[206:209], v[222:225], v[34:37]
	v_mfma_f32_16x16x32_bf16 v[22:25], v[198:201], v[230:233], v[22:25]
	v_mfma_f32_16x16x32_bf16 v[18:21], v[206:209], v[230:233], v[18:21]
	v_mfma_f32_16x16x32_bf16 v[6:9], v[198:201], v[238:241], v[6:9]
	v_mfma_f32_16x16x32_bf16 v[2:5], v[206:209], v[238:241], v[2:5]
	v_mfma_f32_16x16x32_bf16 v[54:57], v[202:205], v[218:221], v[54:57]
	v_mfma_f32_16x16x32_bf16 v[50:53], v[210:213], v[218:221], v[50:53]
	v_mfma_f32_16x16x32_bf16 v[38:41], v[202:205], v[226:229], v[38:41]
	v_mfma_f32_16x16x32_bf16 v[34:37], v[210:213], v[226:229], v[34:37]
	v_mfma_f32_16x16x32_bf16 v[22:25], v[202:205], v[234:237], v[22:25]
	v_mfma_f32_16x16x32_bf16 v[18:21], v[210:213], v[234:237], v[18:21]
	v_mfma_f32_16x16x32_bf16 v[6:9], v[202:205], v[242:245], v[6:9]
	v_mfma_f32_16x16x32_bf16 v[2:5], v[210:213], v[242:245], v[2:5]
	s_barrier
	s_cbranch_scc0 .Lgk_929
	s_and_b64 vcc, exec, s[20:21]
	s_mov_b64 s[62:63], s[14:15]
	s_cbranch_vccz .LBB0_932
	s_barrier
